# attention c=0 steps: first exps of a step issued inside the LDS-latency window in front of the first QK MFMA
# baseline (speedup 1.0000x reference)
.Lst0_u6_loop:
	s_add_i32 s46, s58, 0
	s_mov_b32 m0, s46
	s_nop 0
	global_load_lds_dwordx4 v198, s[98:99]
	s_add_i32 m0, s46, 0x400
	s_nop 0
	global_load_lds_dwordx4 v194, s[98:99]
	s_add_i32 s48, s58, 0x8000
	s_add_i32 m0, s48, 0xc000
	s_nop 0
	global_load_lds_dwordx4 v196, s[100:101]
	s_add_i32 m0, s48, 0xc400
	s_nop 0
	global_load_lds_dwordx4 v192, s[100:101]
	ds_read_b128 v[96:99], v205 offset:16384
	ds_read_b128 v[100:103], v205 offset:24576
	v_exp_f32_e32 v140, v48
	v_exp_f32_e32 v141, v49
	v_exp_f32_e32 v142, v50
	v_exp_f32_e32 v143, v51
	s_waitcnt lgkmcnt(0)
	v_mfma_f32_32x32x16_bf16 v[112:127], v[96:99], v[160:163], 0
	ds_read_b128 v[128:131], v211 offset:16384
	ds_read_b128 v[132:135], v211 offset:24576
	ds_read_b128 v[136:139], v212 offset:16384
	ds_read_b128 v[48:51], v212 offset:24576
	v_mfma_f32_32x32x16_bf16 v[96:111], v[100:103], v[160:163], 0
	v_exp_f32_e32 v144, v52
	v_exp_f32_e32 v145, v53
	v_exp_f32_e32 v146, v54
	v_exp_f32_e32 v147, v55
	s_waitcnt lgkmcnt(0)
	v_mfma_f32_32x32x16_bf16 v[112:127], v[128:131], v[164:167], v[112:127]
	ds_read_b128 v[52:55], v213 offset:16384
	v_exp_f32_e32 v148, v56
	v_exp_f32_e32 v149, v57
	v_exp_f32_e32 v150, v58
	v_exp_f32_e32 v151, v59
	v_mfma_f32_32x32x16_bf16 v[96:111], v[132:135], v[164:167], v[96:111]
	ds_read_b128 v[56:59], v213 offset:24576
	v_exp_f32_e32 v128, v60
	v_exp_f32_e32 v129, v61
	v_exp_f32_e32 v130, v62
	v_exp_f32_e32 v131, v63
	v_mfma_f32_32x32x16_bf16 v[112:127], v[136:139], v[168:171], v[112:127]
	ds_read_b128 v[60:63], v206 offset:49152
	v_exp_f32_e32 v132, v32
	v_exp_f32_e32 v133, v33
	v_exp_f32_e32 v134, v34
	v_exp_f32_e32 v135, v35
	v_mfma_f32_32x32x16_bf16 v[96:111], v[48:51], v[168:171], v[96:111]
	ds_read_b128 v[32:35], v206 offset:53248
	v_exp_f32_e32 v136, v36
	v_exp_f32_e32 v137, v37
	v_exp_f32_e32 v138, v38
	v_exp_f32_e32 v139, v39
	s_waitcnt lgkmcnt(0)
	v_mfma_f32_32x32x16_bf16 v[112:127], v[52:55], v[172:175], v[112:127]
	ds_read_b128 v[36:39], v206 offset:57344
	v_exp_f32_e32 v152, v40
	v_exp_f32_e32 v153, v41
	v_exp_f32_e32 v154, v42
	v_exp_f32_e32 v155, v43
	v_mfma_f32_32x32x16_bf16 v[96:111], v[56:59], v[172:175], v[96:111]
	ds_read_b128 v[40:43], v206 offset:61440
	v_exp_f32_e32 v156, v44
	v_exp_f32_e32 v157, v45
	v_exp_f32_e32 v158, v46
	v_exp_f32_e32 v159, v47
	v_cvt_pk_bf16_f32 v44, v140, v141
	v_cvt_pk_bf16_f32 v45, v142, v143
	v_cvt_pk_bf16_f32 v46, v144, v145
	v_cvt_pk_bf16_f32 v47, v146, v147
	s_nop 1
	v_mfma_f32_32x32x16_bf16 v[80:95], v[60:63], v[44:47], v[80:95]
	ds_read_b128 v[48:51], v207 offset:49152
	v_cvt_pk_bf16_f32 v52, v148, v149
	v_cvt_pk_bf16_f32 v53, v150, v151
	v_cvt_pk_bf16_f32 v54, v128, v129
	v_cvt_pk_bf16_f32 v55, v130, v131
	v_mfma_f32_32x32x16_bf16 v[64:79], v[32:35], v[44:47], v[64:79]
	ds_read_b128 v[56:59], v207 offset:53248
	v_pk_add_f32 v[62:63], v[146:147], v[142:143]
	v_pk_add_f32 v[60:61], v[144:145], v[140:141]
	s_waitcnt lgkmcnt(0)
	v_mfma_f32_32x32x16_bf16 v[16:31], v[36:39], v[44:47], v[16:31]
	ds_read_b128 v[32:35], v207 offset:57344
	v_add_f32_e64 v62, v150, v62
	v_add_f32_e64 v63, v151, v63
	v_add_f32_e64 v60, v148, v60
	v_add_f32_e64 v61, v149, v61
	v_pk_add_f32 v[62:63], v[130:131], v[62:63]
	v_pk_add_f32 v[60:61], v[128:129], v[60:61]
	v_mfma_f32_32x32x16_bf16 v[0:15], v[40:43], v[44:47], v[0:15]
	ds_read_b128 v[36:39], v207 offset:61440
	v_mfma_f32_32x32x16_bf16 v[80:95], v[48:51], v[52:55], v[80:95]
	ds_read_b128 v[40:43], v208 offset:49152
	v_cvt_pk_bf16_f32 v44, v132, v133
	v_cvt_pk_bf16_f32 v45, v134, v135
	v_cvt_pk_bf16_f32 v46, v136, v137
	v_cvt_pk_bf16_f32 v47, v138, v139
	v_mfma_f32_32x32x16_bf16 v[64:79], v[56:59], v[52:55], v[64:79]
	ds_read_b128 v[48:51], v208 offset:53248
	v_add_f32_e64 v62, v134, v62
	v_add_f32_e64 v63, v135, v63
	v_add_f32_e64 v60, v132, v60
	v_add_f32_e64 v61, v133, v61
	v_pk_add_f32 v[62:63], v[138:139], v[62:63]
	v_pk_add_f32 v[60:61], v[136:137], v[60:61]
	s_waitcnt lgkmcnt(0)
	v_mfma_f32_32x32x16_bf16 v[16:31], v[32:35], v[52:55], v[16:31]
	ds_read_b128 v[56:59], v208 offset:57344
	v_add_f32_e64 v62, v154, v62
	v_add_f32_e64 v63, v155, v63
	v_add_f32_e64 v60, v152, v60
	v_add_f32_e64 v61, v153, v61
	v_pk_add_f32 v[130:131], v[158:159], v[62:63]
	v_pk_add_f32 v[128:129], v[156:157], v[60:61]
	v_mfma_f32_32x32x16_bf16 v[0:15], v[36:39], v[52:55], v[0:15]
	ds_read_b128 v[32:35], v208 offset:61440
	v_mfma_f32_32x32x16_bf16 v[80:95], v[40:43], v[44:47], v[80:95]
	ds_read_b128 v[36:39], v209 offset:49152
	v_cvt_pk_bf16_f32 v52, v152, v153
	v_cvt_pk_bf16_f32 v53, v154, v155
	v_cvt_pk_bf16_f32 v54, v156, v157
	v_cvt_pk_bf16_f32 v55, v158, v159
	v_mfma_f32_32x32x16_bf16 v[64:79], v[48:51], v[44:47], v[64:79]
	ds_read_b128 v[40:43], v209 offset:53248
	s_waitcnt lgkmcnt(0)
	v_mfma_f32_32x32x16_bf16 v[16:31], v[56:59], v[44:47], v[16:31]
	ds_read_b128 v[48:51], v209 offset:57344
	v_mfma_f32_32x32x16_bf16 v[0:15], v[32:35], v[44:47], v[0:15]
	ds_read_b128 v[56:59], v209 offset:61440
	v_mfma_f32_32x32x16_bf16 v[80:95], v[36:39], v[52:55], v[80:95]
	v_mfma_f32_32x32x16_bf16 v[64:79], v[40:43], v[52:55], v[64:79]
	s_waitcnt lgkmcnt(0)
	v_mfma_f32_32x32x16_bf16 v[16:31], v[48:51], v[52:55], v[16:31]
	v_mfma_f32_32x32x16_bf16 v[0:15], v[56:59], v[52:55], v[0:15]
	s_waitcnt vmcnt(4) lgkmcnt(0)
	s_barrier
	s_add_u32 s68, s98, 0x18000
	s_addc_u32 s69, s99, 0
	s_add_i32 s49, 0x4000, s57
	s_mov_b32 m0, s49
	s_nop 0
	global_load_lds_dwordx4 v198, s[68:69]
	s_add_i32 m0, s49, 0x400
	s_nop 0
	global_load_lds_dwordx4 v194, s[68:69]
	s_add_u32 s44, s100, 0x80
	s_addc_u32 s45, s101, 0
	s_add_i32 s49, s58, 0xc000
	s_add_i32 m0, s49, 0xc000
	s_nop 0
	global_load_lds_dwordx4 v196, s[44:45]
	s_add_i32 m0, s49, 0xc400
	s_nop 0
	global_load_lds_dwordx4 v192, s[44:45]
	v_exp_f32_e32 v144, v112
	ds_read_b128 v[32:35], v205 offset:32768
	ds_read_b128 v[36:39], v205 offset:40960
	v_exp_f32_e32 v145, v113
	v_exp_f32_e32 v146, v114
	v_exp_f32_e32 v147, v115
	s_waitcnt lgkmcnt(0)
	v_mfma_f32_32x32x16_bf16 v[48:63], v[32:35], v[160:163], 0
	ds_read_b128 v[132:135], v211 offset:32768
	ds_read_b128 v[136:139], v211 offset:40960
	ds_read_b128 v[140:143], v212 offset:32768
	ds_read_b128 v[112:115], v212 offset:40960
	v_mfma_f32_32x32x16_bf16 v[32:47], v[36:39], v[160:163], 0
	v_exp_f32_e32 v148, v116
	v_exp_f32_e32 v149, v117
	v_exp_f32_e32 v150, v118
	v_exp_f32_e32 v151, v119
	s_waitcnt lgkmcnt(0)
	v_mfma_f32_32x32x16_bf16 v[48:63], v[132:135], v[164:167], v[48:63]
	ds_read_b128 v[116:119], v213 offset:32768
	v_exp_f32_e32 v152, v120
	v_exp_f32_e32 v153, v121
	v_exp_f32_e32 v154, v122
	v_exp_f32_e32 v155, v123
	v_mfma_f32_32x32x16_bf16 v[32:47], v[136:139], v[164:167], v[32:47]
	ds_read_b128 v[120:123], v213 offset:40960
	v_exp_f32_e32 v156, v124
	v_exp_f32_e32 v157, v125
	v_exp_f32_e32 v158, v126
	v_exp_f32_e32 v159, v127
	v_mfma_f32_32x32x16_bf16 v[48:63], v[140:143], v[168:171], v[48:63]
	ds_read_b128 v[124:127], v236
	v_exp_f32_e32 v136, v96
	v_exp_f32_e32 v137, v97
	v_exp_f32_e32 v138, v98
	v_exp_f32_e32 v139, v99
	v_mfma_f32_32x32x16_bf16 v[32:47], v[112:115], v[168:171], v[32:47]
	ds_read_b128 v[96:99], v236 offset:4096
	v_exp_f32_e32 v140, v100
	v_exp_f32_e32 v141, v101
	v_exp_f32_e32 v142, v102
	v_exp_f32_e32 v143, v103
	s_waitcnt lgkmcnt(0)
	v_mfma_f32_32x32x16_bf16 v[48:63], v[116:119], v[172:175], v[48:63]
	ds_read_b128 v[100:103], v236 offset:8192
	v_exp_f32_e32 v178, v104
	v_exp_f32_e32 v179, v105
	v_exp_f32_e32 v180, v106
	v_exp_f32_e32 v181, v107
	v_mfma_f32_32x32x16_bf16 v[32:47], v[120:123], v[172:175], v[32:47]
	ds_read_b128 v[104:107], v236 offset:12288
	v_exp_f32_e32 v182, v108
	v_exp_f32_e32 v183, v109
	v_exp_f32_e32 v184, v110
	v_exp_f32_e32 v185, v111
	v_cvt_pk_bf16_f32 v108, v144, v145
	v_cvt_pk_bf16_f32 v109, v146, v147
	v_cvt_pk_bf16_f32 v110, v148, v149
	v_cvt_pk_bf16_f32 v111, v150, v151
	s_nop 1
	v_mfma_f32_32x32x16_bf16 v[80:95], v[124:127], v[108:111], v[80:95]
	ds_read_b128 v[112:115], v237
	v_cvt_pk_bf16_f32 v116, v152, v153
	v_cvt_pk_bf16_f32 v117, v154, v155
	v_cvt_pk_bf16_f32 v118, v156, v157
	v_cvt_pk_bf16_f32 v119, v158, v159
	v_mfma_f32_32x32x16_bf16 v[64:79], v[96:99], v[108:111], v[64:79]
	ds_read_b128 v[120:123], v237 offset:4096
	v_pk_add_f32 v[126:127], v[150:151], v[146:147]
	v_pk_add_f32 v[124:125], v[148:149], v[144:145]
	s_waitcnt lgkmcnt(0)
	v_mfma_f32_32x32x16_bf16 v[16:31], v[100:103], v[108:111], v[16:31]
	ds_read_b128 v[132:135], v237 offset:8192
	v_add_f32_e64 v98, v154, v126
	v_add_f32_e64 v99, v155, v127
	v_add_f32_e64 v96, v152, v124
	v_add_f32_e64 v97, v153, v125
	v_pk_add_f32 v[98:99], v[158:159], v[98:99]
	v_pk_add_f32 v[96:97], v[156:157], v[96:97]
	v_mfma_f32_32x32x16_bf16 v[0:15], v[104:107], v[108:111], v[0:15]
	ds_read_b128 v[100:103], v237 offset:12288
	v_mfma_f32_32x32x16_bf16 v[80:95], v[112:115], v[116:119], v[80:95]
	ds_read_b128 v[104:107], v238
	v_cvt_pk_bf16_f32 v108, v136, v137
	v_cvt_pk_bf16_f32 v109, v138, v139
	v_cvt_pk_bf16_f32 v110, v140, v141
	v_cvt_pk_bf16_f32 v111, v142, v143
	v_mfma_f32_32x32x16_bf16 v[64:79], v[120:123], v[116:119], v[64:79]
	ds_read_b128 v[112:115], v238 offset:4096
	v_add_f32_e64 v98, v138, v98
	v_add_f32_e64 v99, v139, v99
	v_add_f32_e64 v96, v136, v96
	v_add_f32_e64 v97, v137, v97
	v_pk_add_f32 v[98:99], v[142:143], v[98:99]
	v_pk_add_f32 v[96:97], v[140:141], v[96:97]
	s_waitcnt lgkmcnt(0)
	v_mfma_f32_32x32x16_bf16 v[16:31], v[132:135], v[116:119], v[16:31]
	ds_read_b128 v[120:123], v238 offset:8192
	v_add_f32_e64 v98, v180, v98
	v_add_f32_e64 v99, v181, v99
	v_add_f32_e64 v96, v178, v96
	v_add_f32_e64 v97, v179, v97
	v_pk_add_f32 v[98:99], v[184:185], v[98:99]
	v_pk_add_f32 v[96:97], v[182:183], v[96:97]
	v_mfma_f32_32x32x16_bf16 v[0:15], v[100:103], v[116:119], v[0:15]
	ds_read_b128 v[124:127], v238 offset:12288
	v_mfma_f32_32x32x16_bf16 v[80:95], v[104:107], v[108:111], v[80:95]
	ds_read_b128 v[100:103], v239
	v_cvt_pk_bf16_f32 v116, v178, v179
	v_cvt_pk_bf16_f32 v117, v180, v181
	v_cvt_pk_bf16_f32 v118, v182, v183
	v_cvt_pk_bf16_f32 v119, v184, v185
	v_mfma_f32_32x32x16_bf16 v[64:79], v[112:115], v[108:111], v[64:79]
	ds_read_b128 v[104:107], v239 offset:4096
	s_waitcnt lgkmcnt(0)
	v_mfma_f32_32x32x16_bf16 v[16:31], v[120:123], v[108:111], v[16:31]
	ds_read_b128 v[112:115], v239 offset:8192
	v_mfma_f32_32x32x16_bf16 v[0:15], v[124:127], v[108:111], v[0:15]
	ds_read_b128 v[120:123], v239 offset:12288
	v_mfma_f32_32x32x16_bf16 v[80:95], v[100:103], v[116:119], v[80:95]
	v_mfma_f32_32x32x16_bf16 v[64:79], v[104:107], v[116:119], v[64:79]
	s_waitcnt lgkmcnt(0)
	v_mfma_f32_32x32x16_bf16 v[16:31], v[112:115], v[116:119], v[16:31]
	v_mfma_f32_32x32x16_bf16 v[0:15], v[120:123], v[116:119], v[0:15]
	s_waitcnt vmcnt(4) lgkmcnt(0)
	v_add_f32_e32 v100, v128, v129
	v_add_f32_e32 v101, v130, v131
	v_add_f32_e32 v100, v100, v101
	v_add_f32_e32 v96, v96, v97
	v_add_f32_e32 v97, v98, v99
	s_barrier
	v_add_f32_e32 v100, v177, v100
	v_add_f32_e32 v96, v96, v97
	v_add_f32_e32 v177, v100, v96
	s_add_u32 s98, s98, 0x30000
	s_addc_u32 s99, s99, 0
	s_add_u32 s100, s100, 0x100
	s_addc_u32 s101, s101, 0
	s_add_i32 s46, s58, 0x8000
	s_mov_b32 m0, s46
	s_nop 0
	global_load_lds_dwordx4 v198, s[98:99]
	s_add_i32 m0, s46, 0x400
	s_nop 0
	global_load_lds_dwordx4 v194, s[98:99]
	s_add_i32 s48, s58, 0
	s_add_i32 m0, s48, 0xc000
	s_nop 0
	global_load_lds_dwordx4 v196, s[100:101]
	s_add_i32 m0, s48, 0xc400
	s_nop 0
	global_load_lds_dwordx4 v192, s[100:101]
	ds_read_b128 v[96:99], v205
	ds_read_b128 v[100:103], v205 offset:8192
	v_exp_f32_e32 v140, v48
	v_exp_f32_e32 v141, v49
	v_exp_f32_e32 v142, v50
	v_exp_f32_e32 v143, v51
	s_waitcnt lgkmcnt(0)
	v_mfma_f32_32x32x16_bf16 v[112:127], v[96:99], v[160:163], 0
	ds_read_b128 v[128:131], v211
	ds_read_b128 v[132:135], v211 offset:8192
	ds_read_b128 v[136:139], v212
	ds_read_b128 v[48:51], v212 offset:8192
	v_mfma_f32_32x32x16_bf16 v[96:111], v[100:103], v[160:163], 0
	v_exp_f32_e32 v144, v52
	v_exp_f32_e32 v145, v53
	v_exp_f32_e32 v146, v54
	v_exp_f32_e32 v147, v55
	s_waitcnt lgkmcnt(0)
	v_mfma_f32_32x32x16_bf16 v[112:127], v[128:131], v[164:167], v[112:127]
	ds_read_b128 v[52:55], v213
	v_exp_f32_e32 v148, v56
	v_exp_f32_e32 v149, v57
	v_exp_f32_e32 v150, v58
	v_exp_f32_e32 v151, v59
	v_mfma_f32_32x32x16_bf16 v[96:111], v[132:135], v[164:167], v[96:111]
	ds_read_b128 v[56:59], v213 offset:8192
	v_exp_f32_e32 v128, v60
	v_exp_f32_e32 v129, v61
	v_exp_f32_e32 v130, v62
	v_exp_f32_e32 v131, v63
	v_mfma_f32_32x32x16_bf16 v[112:127], v[136:139], v[168:171], v[112:127]
	ds_read_b128 v[60:63], v236 offset:16384
	v_exp_f32_e32 v132, v32
	v_exp_f32_e32 v133, v33
	v_exp_f32_e32 v134, v34
	v_exp_f32_e32 v135, v35
	v_mfma_f32_32x32x16_bf16 v[96:111], v[48:51], v[168:171], v[96:111]
	ds_read_b128 v[32:35], v236 offset:20480
	v_exp_f32_e32 v136, v36
	v_exp_f32_e32 v137, v37
	v_exp_f32_e32 v138, v38
	v_exp_f32_e32 v139, v39
	s_waitcnt lgkmcnt(0)
	v_mfma_f32_32x32x16_bf16 v[112:127], v[52:55], v[172:175], v[112:127]
	ds_read_b128 v[36:39], v236 offset:24576
	v_exp_f32_e32 v152, v40
	v_exp_f32_e32 v153, v41
	v_exp_f32_e32 v154, v42
	v_exp_f32_e32 v155, v43
	v_mfma_f32_32x32x16_bf16 v[96:111], v[56:59], v[172:175], v[96:111]
	ds_read_b128 v[40:43], v236 offset:28672
	v_exp_f32_e32 v156, v44
	v_exp_f32_e32 v157, v45
	v_exp_f32_e32 v158, v46
	v_exp_f32_e32 v159, v47
	v_cvt_pk_bf16_f32 v44, v140, v141
	v_cvt_pk_bf16_f32 v45, v142, v143
	v_cvt_pk_bf16_f32 v46, v144, v145
	v_cvt_pk_bf16_f32 v47, v146, v147
	s_nop 1
	v_mfma_f32_32x32x16_bf16 v[80:95], v[60:63], v[44:47], v[80:95]
	ds_read_b128 v[48:51], v237 offset:16384
	v_cvt_pk_bf16_f32 v52, v148, v149
	v_cvt_pk_bf16_f32 v53, v150, v151
	v_cvt_pk_bf16_f32 v54, v128, v129
	v_cvt_pk_bf16_f32 v55, v130, v131
	v_mfma_f32_32x32x16_bf16 v[64:79], v[32:35], v[44:47], v[64:79]
	ds_read_b128 v[56:59], v237 offset:20480
	v_pk_add_f32 v[62:63], v[146:147], v[142:143]
	v_pk_add_f32 v[60:61], v[144:145], v[140:141]
	s_waitcnt lgkmcnt(0)
	v_mfma_f32_32x32x16_bf16 v[16:31], v[36:39], v[44:47], v[16:31]
	ds_read_b128 v[32:35], v237 offset:24576
	v_add_f32_e64 v62, v150, v62
	v_add_f32_e64 v63, v151, v63
	v_add_f32_e64 v60, v148, v60
	v_add_f32_e64 v61, v149, v61
	v_pk_add_f32 v[62:63], v[130:131], v[62:63]
	v_pk_add_f32 v[60:61], v[128:129], v[60:61]
	v_mfma_f32_32x32x16_bf16 v[0:15], v[40:43], v[44:47], v[0:15]
	ds_read_b128 v[36:39], v237 offset:28672
	v_mfma_f32_32x32x16_bf16 v[80:95], v[48:51], v[52:55], v[80:95]
	ds_read_b128 v[40:43], v238 offset:16384
	v_cvt_pk_bf16_f32 v44, v132, v133
	v_cvt_pk_bf16_f32 v45, v134, v135
	v_cvt_pk_bf16_f32 v46, v136, v137
	v_cvt_pk_bf16_f32 v47, v138, v139
	v_mfma_f32_32x32x16_bf16 v[64:79], v[56:59], v[52:55], v[64:79]
	ds_read_b128 v[48:51], v238 offset:20480
	v_add_f32_e64 v62, v134, v62
	v_add_f32_e64 v63, v135, v63
	v_add_f32_e64 v60, v132, v60
	v_add_f32_e64 v61, v133, v61
	v_pk_add_f32 v[62:63], v[138:139], v[62:63]
	v_pk_add_f32 v[60:61], v[136:137], v[60:61]
	s_waitcnt lgkmcnt(0)
	v_mfma_f32_32x32x16_bf16 v[16:31], v[32:35], v[52:55], v[16:31]
	ds_read_b128 v[56:59], v238 offset:24576
	v_add_f32_e64 v62, v154, v62
	v_add_f32_e64 v63, v155, v63
	v_add_f32_e64 v60, v152, v60
	v_add_f32_e64 v61, v153, v61
	v_pk_add_f32 v[130:131], v[158:159], v[62:63]
	v_pk_add_f32 v[128:129], v[156:157], v[60:61]
	v_mfma_f32_32x32x16_bf16 v[0:15], v[36:39], v[52:55], v[0:15]
	ds_read_b128 v[32:35], v238 offset:28672
	v_mfma_f32_32x32x16_bf16 v[80:95], v[40:43], v[44:47], v[80:95]
	ds_read_b128 v[36:39], v239 offset:16384
	v_cvt_pk_bf16_f32 v52, v152, v153
	v_cvt_pk_bf16_f32 v53, v154, v155
	v_cvt_pk_bf16_f32 v54, v156, v157
	v_cvt_pk_bf16_f32 v55, v158, v159
	v_mfma_f32_32x32x16_bf16 v[64:79], v[48:51], v[44:47], v[64:79]
	ds_read_b128 v[40:43], v239 offset:20480
	s_waitcnt lgkmcnt(0)
	v_mfma_f32_32x32x16_bf16 v[16:31], v[56:59], v[44:47], v[16:31]
	ds_read_b128 v[48:51], v239 offset:24576
	v_mfma_f32_32x32x16_bf16 v[0:15], v[32:35], v[44:47], v[0:15]
	ds_read_b128 v[56:59], v239 offset:28672
	v_mfma_f32_32x32x16_bf16 v[80:95], v[36:39], v[52:55], v[80:95]
	v_mfma_f32_32x32x16_bf16 v[64:79], v[40:43], v[52:55], v[64:79]
	s_waitcnt lgkmcnt(0)
	v_mfma_f32_32x32x16_bf16 v[16:31], v[48:51], v[52:55], v[16:31]
	v_mfma_f32_32x32x16_bf16 v[0:15], v[56:59], v[52:55], v[0:15]
	s_waitcnt vmcnt(4) lgkmcnt(0)
	s_barrier
	s_add_u32 s68, s98, 0x18000
	s_addc_u32 s69, s99, 0
	s_add_i32 s49, 0, s57
	s_mov_b32 m0, s49
	s_nop 0
	global_load_lds_dwordx4 v198, s[68:69]
	s_add_i32 m0, s49, 0x400
	s_nop 0
	global_load_lds_dwordx4 v194, s[68:69]
	s_add_u32 s44, s100, 0x80
	s_addc_u32 s45, s101, 0
	s_add_i32 s49, s58, 0x4000
	s_add_i32 m0, s49, 0xc000
	s_nop 0
	global_load_lds_dwordx4 v196, s[44:45]
	s_add_i32 m0, s49, 0xc400
	s_nop 0
	global_load_lds_dwordx4 v192, s[44:45]
	v_exp_f32_e32 v144, v112
	ds_read_b128 v[32:35], v205 offset:16384
	ds_read_b128 v[36:39], v205 offset:24576
	v_exp_f32_e32 v145, v113
	v_exp_f32_e32 v146, v114
	v_exp_f32_e32 v147, v115
	s_waitcnt lgkmcnt(0)
	v_mfma_f32_32x32x16_bf16 v[48:63], v[32:35], v[160:163], 0
	ds_read_b128 v[132:135], v211 offset:16384
	ds_read_b128 v[136:139], v211 offset:24576
	ds_read_b128 v[140:143], v212 offset:16384
	ds_read_b128 v[112:115], v212 offset:24576
	v_mfma_f32_32x32x16_bf16 v[32:47], v[36:39], v[160:163], 0
	v_exp_f32_e32 v148, v116
	v_exp_f32_e32 v149, v117
	v_exp_f32_e32 v150, v118
	v_exp_f32_e32 v151, v119
	s_waitcnt lgkmcnt(0)
	v_mfma_f32_32x32x16_bf16 v[48:63], v[132:135], v[164:167], v[48:63]
	ds_read_b128 v[116:119], v213 offset:16384
	v_exp_f32_e32 v152, v120
	v_exp_f32_e32 v153, v121
	v_exp_f32_e32 v154, v122
	v_exp_f32_e32 v155, v123
	v_mfma_f32_32x32x16_bf16 v[32:47], v[136:139], v[164:167], v[32:47]
	ds_read_b128 v[120:123], v213 offset:24576
	v_exp_f32_e32 v156, v124
	v_exp_f32_e32 v157, v125
	v_exp_f32_e32 v158, v126
	v_exp_f32_e32 v159, v127
	v_mfma_f32_32x32x16_bf16 v[48:63], v[140:143], v[168:171], v[48:63]
	ds_read_b128 v[124:127], v236 offset:32768
	v_exp_f32_e32 v136, v96
	v_exp_f32_e32 v137, v97
	v_exp_f32_e32 v138, v98
	v_exp_f32_e32 v139, v99
	v_mfma_f32_32x32x16_bf16 v[32:47], v[112:115], v[168:171], v[32:47]
	ds_read_b128 v[96:99], v236 offset:36864
	v_exp_f32_e32 v140, v100
	v_exp_f32_e32 v141, v101
	v_exp_f32_e32 v142, v102
	v_exp_f32_e32 v143, v103
	s_waitcnt lgkmcnt(0)
	v_mfma_f32_32x32x16_bf16 v[48:63], v[116:119], v[172:175], v[48:63]
	ds_read_b128 v[100:103], v236 offset:40960
	v_exp_f32_e32 v178, v104
	v_exp_f32_e32 v179, v105
	v_exp_f32_e32 v180, v106
	v_exp_f32_e32 v181, v107
	v_mfma_f32_32x32x16_bf16 v[32:47], v[120:123], v[172:175], v[32:47]
	ds_read_b128 v[104:107], v236 offset:45056
	v_exp_f32_e32 v182, v108
	v_exp_f32_e32 v183, v109
	v_exp_f32_e32 v184, v110
	v_exp_f32_e32 v185, v111
	v_cvt_pk_bf16_f32 v108, v144, v145
	v_cvt_pk_bf16_f32 v109, v146, v147
	v_cvt_pk_bf16_f32 v110, v148, v149
	v_cvt_pk_bf16_f32 v111, v150, v151
	s_nop 1
	v_mfma_f32_32x32x16_bf16 v[80:95], v[124:127], v[108:111], v[80:95]
	ds_read_b128 v[112:115], v237 offset:32768
	v_cvt_pk_bf16_f32 v116, v152, v153
	v_cvt_pk_bf16_f32 v117, v154, v155
	v_cvt_pk_bf16_f32 v118, v156, v157
	v_cvt_pk_bf16_f32 v119, v158, v159
	v_mfma_f32_32x32x16_bf16 v[64:79], v[96:99], v[108:111], v[64:79]
	ds_read_b128 v[120:123], v237 offset:36864
	v_pk_add_f32 v[126:127], v[150:151], v[146:147]
	v_pk_add_f32 v[124:125], v[148:149], v[144:145]
	s_waitcnt lgkmcnt(0)
	v_mfma_f32_32x32x16_bf16 v[16:31], v[100:103], v[108:111], v[16:31]
	ds_read_b128 v[132:135], v237 offset:40960
	v_add_f32_e64 v98, v154, v126
	v_add_f32_e64 v99, v155, v127
	v_add_f32_e64 v96, v152, v124
	v_add_f32_e64 v97, v153, v125
	v_pk_add_f32 v[98:99], v[158:159], v[98:99]
	v_pk_add_f32 v[96:97], v[156:157], v[96:97]
	v_mfma_f32_32x32x16_bf16 v[0:15], v[104:107], v[108:111], v[0:15]
	ds_read_b128 v[100:103], v237 offset:45056
	v_mfma_f32_32x32x16_bf16 v[80:95], v[112:115], v[116:119], v[80:95]
	ds_read_b128 v[104:107], v238 offset:32768
	v_cvt_pk_bf16_f32 v108, v136, v137
	v_cvt_pk_bf16_f32 v109, v138, v139
	v_cvt_pk_bf16_f32 v110, v140, v141
	v_cvt_pk_bf16_f32 v111, v142, v143
	v_mfma_f32_32x32x16_bf16 v[64:79], v[120:123], v[116:119], v[64:79]
	ds_read_b128 v[112:115], v238 offset:36864
	v_add_f32_e64 v98, v138, v98
	v_add_f32_e64 v99, v139, v99
	v_add_f32_e64 v96, v136, v96
	v_add_f32_e64 v97, v137, v97
	v_pk_add_f32 v[98:99], v[142:143], v[98:99]
	v_pk_add_f32 v[96:97], v[140:141], v[96:97]
	s_waitcnt lgkmcnt(0)
	v_mfma_f32_32x32x16_bf16 v[16:31], v[132:135], v[116:119], v[16:31]
	ds_read_b128 v[120:123], v238 offset:40960
	v_add_f32_e64 v98, v180, v98
	v_add_f32_e64 v99, v181, v99
	v_add_f32_e64 v96, v178, v96
	v_add_f32_e64 v97, v179, v97
	v_pk_add_f32 v[98:99], v[184:185], v[98:99]
	v_pk_add_f32 v[96:97], v[182:183], v[96:97]
	v_mfma_f32_32x32x16_bf16 v[0:15], v[100:103], v[116:119], v[0:15]
	ds_read_b128 v[124:127], v238 offset:45056
	v_mfma_f32_32x32x16_bf16 v[80:95], v[104:107], v[108:111], v[80:95]
	ds_read_b128 v[100:103], v239 offset:32768
	v_cvt_pk_bf16_f32 v116, v178, v179
	v_cvt_pk_bf16_f32 v117, v180, v181
	v_cvt_pk_bf16_f32 v118, v182, v183
	v_cvt_pk_bf16_f32 v119, v184, v185
	v_mfma_f32_32x32x16_bf16 v[64:79], v[112:115], v[108:111], v[64:79]
	ds_read_b128 v[104:107], v239 offset:36864
	s_waitcnt lgkmcnt(0)
	v_mfma_f32_32x32x16_bf16 v[16:31], v[120:123], v[108:111], v[16:31]
	ds_read_b128 v[112:115], v239 offset:40960
	v_mfma_f32_32x32x16_bf16 v[0:15], v[124:127], v[108:111], v[0:15]
	ds_read_b128 v[120:123], v239 offset:45056
	v_mfma_f32_32x32x16_bf16 v[80:95], v[100:103], v[116:119], v[80:95]
	v_mfma_f32_32x32x16_bf16 v[64:79], v[104:107], v[116:119], v[64:79]
	s_waitcnt lgkmcnt(0)
	v_mfma_f32_32x32x16_bf16 v[16:31], v[112:115], v[116:119], v[16:31]
	v_mfma_f32_32x32x16_bf16 v[0:15], v[120:123], v[116:119], v[0:15]
	s_waitcnt vmcnt(4) lgkmcnt(0)
	v_add_f32_e32 v100, v128, v129
	v_add_f32_e32 v101, v130, v131
	v_add_f32_e32 v100, v100, v101
	v_add_f32_e32 v96, v96, v97
	v_add_f32_e32 v97, v98, v99
	s_barrier
	v_add_f32_e32 v100, v177, v100
	v_add_f32_e32 v96, v96, v97
	v_add_f32_e32 v177, v100, v96
	s_add_u32 s98, s98, 0x30000
	s_addc_u32 s99, s99, 0
	s_add_u32 s100, s100, 0x100
	s_addc_u32 s101, s101, 0
	s_add_i32 s46, s58, 0x4000
	s_mov_b32 m0, s46
	s_nop 0
	global_load_lds_dwordx4 v198, s[98:99]
	s_add_i32 m0, s46, 0x400
	s_nop 0
	global_load_lds_dwordx4 v194, s[98:99]
	s_add_i32 s48, s58, 0x8000
	s_add_i32 m0, s48, 0xc000
	s_nop 0
	global_load_lds_dwordx4 v196, s[100:101]
	s_add_i32 m0, s48, 0xc400
	s_nop 0
	global_load_lds_dwordx4 v192, s[100:101]
	ds_read_b128 v[96:99], v205 offset:32768
	ds_read_b128 v[100:103], v205 offset:40960
	v_exp_f32_e32 v140, v48
	v_exp_f32_e32 v141, v49
	v_exp_f32_e32 v142, v50
	v_exp_f32_e32 v143, v51
	s_waitcnt lgkmcnt(0)
	v_mfma_f32_32x32x16_bf16 v[112:127], v[96:99], v[160:163], 0
	ds_read_b128 v[128:131], v211 offset:32768
	ds_read_b128 v[132:135], v211 offset:40960
	ds_read_b128 v[136:139], v212 offset:32768
	ds_read_b128 v[48:51], v212 offset:40960
	v_mfma_f32_32x32x16_bf16 v[96:111], v[100:103], v[160:163], 0
	v_exp_f32_e32 v144, v52
	v_exp_f32_e32 v145, v53
	v_exp_f32_e32 v146, v54
	v_exp_f32_e32 v147, v55
	s_waitcnt lgkmcnt(0)
	v_mfma_f32_32x32x16_bf16 v[112:127], v[128:131], v[164:167], v[112:127]
	ds_read_b128 v[52:55], v213 offset:32768
	v_exp_f32_e32 v148, v56
	v_exp_f32_e32 v149, v57
	v_exp_f32_e32 v150, v58
	v_exp_f32_e32 v151, v59
	v_mfma_f32_32x32x16_bf16 v[96:111], v[132:135], v[164:167], v[96:111]
	ds_read_b128 v[56:59], v213 offset:40960
	v_exp_f32_e32 v128, v60
	v_exp_f32_e32 v129, v61
	v_exp_f32_e32 v130, v62
	v_exp_f32_e32 v131, v63
	v_mfma_f32_32x32x16_bf16 v[112:127], v[136:139], v[168:171], v[112:127]
	ds_read_b128 v[60:63], v206 offset:49152
	v_exp_f32_e32 v132, v32
	v_exp_f32_e32 v133, v33
	v_exp_f32_e32 v134, v34
	v_exp_f32_e32 v135, v35
	v_mfma_f32_32x32x16_bf16 v[96:111], v[48:51], v[168:171], v[96:111]
	ds_read_b128 v[32:35], v206 offset:53248
	v_exp_f32_e32 v136, v36
	v_exp_f32_e32 v137, v37
	v_exp_f32_e32 v138, v38
	v_exp_f32_e32 v139, v39
	s_waitcnt lgkmcnt(0)
	v_mfma_f32_32x32x16_bf16 v[112:127], v[52:55], v[172:175], v[112:127]
	ds_read_b128 v[36:39], v206 offset:57344
	v_exp_f32_e32 v152, v40
	v_exp_f32_e32 v153, v41
	v_exp_f32_e32 v154, v42
	v_exp_f32_e32 v155, v43
	v_mfma_f32_32x32x16_bf16 v[96:111], v[56:59], v[172:175], v[96:111]
	ds_read_b128 v[40:43], v206 offset:61440
	v_exp_f32_e32 v156, v44
	v_exp_f32_e32 v157, v45
	v_exp_f32_e32 v158, v46
	v_exp_f32_e32 v159, v47
	v_cvt_pk_bf16_f32 v44, v140, v141
	v_cvt_pk_bf16_f32 v45, v142, v143
	v_cvt_pk_bf16_f32 v46, v144, v145
	v_cvt_pk_bf16_f32 v47, v146, v147
	s_nop 1
	v_mfma_f32_32x32x16_bf16 v[80:95], v[60:63], v[44:47], v[80:95]
	ds_read_b128 v[48:51], v207 offset:49152
	v_cvt_pk_bf16_f32 v52, v148, v149
	v_cvt_pk_bf16_f32 v53, v150, v151
	v_cvt_pk_bf16_f32 v54, v128, v129
	v_cvt_pk_bf16_f32 v55, v130, v131
	v_mfma_f32_32x32x16_bf16 v[64:79], v[32:35], v[44:47], v[64:79]
	ds_read_b128 v[56:59], v207 offset:53248
	v_pk_add_f32 v[62:63], v[146:147], v[142:143]
	v_pk_add_f32 v[60:61], v[144:145], v[140:141]
	s_waitcnt lgkmcnt(0)
	v_mfma_f32_32x32x16_bf16 v[16:31], v[36:39], v[44:47], v[16:31]
	ds_read_b128 v[32:35], v207 offset:57344
	v_add_f32_e64 v62, v150, v62
	v_add_f32_e64 v63, v151, v63
	v_add_f32_e64 v60, v148, v60
	v_add_f32_e64 v61, v149, v61
	v_pk_add_f32 v[62:63], v[130:131], v[62:63]
	v_pk_add_f32 v[60:61], v[128:129], v[60:61]
	v_mfma_f32_32x32x16_bf16 v[0:15], v[40:43], v[44:47], v[0:15]
	ds_read_b128 v[36:39], v207 offset:61440
	v_mfma_f32_32x32x16_bf16 v[80:95], v[48:51], v[52:55], v[80:95]
	ds_read_b128 v[40:43], v208 offset:49152
	v_cvt_pk_bf16_f32 v44, v132, v133
	v_cvt_pk_bf16_f32 v45, v134, v135
	v_cvt_pk_bf16_f32 v46, v136, v137
	v_cvt_pk_bf16_f32 v47, v138, v139
	v_mfma_f32_32x32x16_bf16 v[64:79], v[56:59], v[52:55], v[64:79]
	ds_read_b128 v[48:51], v208 offset:53248
	v_add_f32_e64 v62, v134, v62
	v_add_f32_e64 v63, v135, v63
	v_add_f32_e64 v60, v132, v60
	v_add_f32_e64 v61, v133, v61
	v_pk_add_f32 v[62:63], v[138:139], v[62:63]
	v_pk_add_f32 v[60:61], v[136:137], v[60:61]
	s_waitcnt lgkmcnt(0)
	v_mfma_f32_32x32x16_bf16 v[16:31], v[32:35], v[52:55], v[16:31]
	ds_read_b128 v[56:59], v208 offset:57344
	v_add_f32_e64 v62, v154, v62
	v_add_f32_e64 v63, v155, v63
	v_add_f32_e64 v60, v152, v60
	v_add_f32_e64 v61, v153, v61
	v_pk_add_f32 v[130:131], v[158:159], v[62:63]
	v_pk_add_f32 v[128:129], v[156:157], v[60:61]
	v_mfma_f32_32x32x16_bf16 v[0:15], v[36:39], v[52:55], v[0:15]
	ds_read_b128 v[32:35], v208 offset:61440
	v_mfma_f32_32x32x16_bf16 v[80:95], v[40:43], v[44:47], v[80:95]
	ds_read_b128 v[36:39], v209 offset:49152
	v_cvt_pk_bf16_f32 v52, v152, v153
	v_cvt_pk_bf16_f32 v53, v154, v155
	v_cvt_pk_bf16_f32 v54, v156, v157
	v_cvt_pk_bf16_f32 v55, v158, v159
	v_mfma_f32_32x32x16_bf16 v[64:79], v[48:51], v[44:47], v[64:79]
	ds_read_b128 v[40:43], v209 offset:53248
	s_waitcnt lgkmcnt(0)
	v_mfma_f32_32x32x16_bf16 v[16:31], v[56:59], v[44:47], v[16:31]
	ds_read_b128 v[48:51], v209 offset:57344
	v_mfma_f32_32x32x16_bf16 v[0:15], v[32:35], v[44:47], v[0:15]
	ds_read_b128 v[56:59], v209 offset:61440
	v_mfma_f32_32x32x16_bf16 v[80:95], v[36:39], v[52:55], v[80:95]
	v_mfma_f32_32x32x16_bf16 v[64:79], v[40:43], v[52:55], v[64:79]
	s_waitcnt lgkmcnt(0)
	v_mfma_f32_32x32x16_bf16 v[16:31], v[48:51], v[52:55], v[16:31]
	v_mfma_f32_32x32x16_bf16 v[0:15], v[56:59], v[52:55], v[0:15]
	s_waitcnt vmcnt(4) lgkmcnt(0)
	s_barrier
	s_add_u32 s68, s98, 0x18000
	s_addc_u32 s69, s99, 0
	s_add_i32 s49, 0x8000, s57
	s_mov_b32 m0, s49
	s_nop 0
	global_load_lds_dwordx4 v198, s[68:69]
	s_add_i32 m0, s49, 0x400
	s_nop 0
	global_load_lds_dwordx4 v194, s[68:69]
	s_add_u32 s44, s100, 0x80
	s_addc_u32 s45, s101, 0
	s_add_i32 s49, s58, 0xc000
	s_add_i32 m0, s49, 0xc000
	s_nop 0
	global_load_lds_dwordx4 v196, s[44:45]
	s_add_i32 m0, s49, 0xc400
	s_nop 0
	global_load_lds_dwordx4 v192, s[44:45]
	v_exp_f32_e32 v144, v112
	ds_read_b128 v[32:35], v205
	ds_read_b128 v[36:39], v205 offset:8192
	v_exp_f32_e32 v145, v113
	v_exp_f32_e32 v146, v114
	v_exp_f32_e32 v147, v115
	s_waitcnt lgkmcnt(0)
	v_mfma_f32_32x32x16_bf16 v[48:63], v[32:35], v[160:163], 0
	ds_read_b128 v[132:135], v211
	ds_read_b128 v[136:139], v211 offset:8192
	ds_read_b128 v[140:143], v212
	ds_read_b128 v[112:115], v212 offset:8192
	v_mfma_f32_32x32x16_bf16 v[32:47], v[36:39], v[160:163], 0
	v_exp_f32_e32 v148, v116
	v_exp_f32_e32 v149, v117
	v_exp_f32_e32 v150, v118
	v_exp_f32_e32 v151, v119
	s_waitcnt lgkmcnt(0)
	v_mfma_f32_32x32x16_bf16 v[48:63], v[132:135], v[164:167], v[48:63]
	ds_read_b128 v[116:119], v213
	v_exp_f32_e32 v152, v120
	v_exp_f32_e32 v153, v121
	v_exp_f32_e32 v154, v122
	v_exp_f32_e32 v155, v123
	v_mfma_f32_32x32x16_bf16 v[32:47], v[136:139], v[164:167], v[32:47]
	ds_read_b128 v[120:123], v213 offset:8192
	v_exp_f32_e32 v156, v124
	v_exp_f32_e32 v157, v125
	v_exp_f32_e32 v158, v126
	v_exp_f32_e32 v159, v127
	v_mfma_f32_32x32x16_bf16 v[48:63], v[140:143], v[168:171], v[48:63]
	ds_read_b128 v[124:127], v236
	v_exp_f32_e32 v136, v96
	v_exp_f32_e32 v137, v97
	v_exp_f32_e32 v138, v98
	v_exp_f32_e32 v139, v99
	v_mfma_f32_32x32x16_bf16 v[32:47], v[112:115], v[168:171], v[32:47]
	ds_read_b128 v[96:99], v236 offset:4096
	v_exp_f32_e32 v140, v100
	v_exp_f32_e32 v141, v101
	v_exp_f32_e32 v142, v102
	v_exp_f32_e32 v143, v103
	s_waitcnt lgkmcnt(0)
	v_mfma_f32_32x32x16_bf16 v[48:63], v[116:119], v[172:175], v[48:63]
	ds_read_b128 v[100:103], v236 offset:8192
	v_exp_f32_e32 v178, v104
	v_exp_f32_e32 v179, v105
	v_exp_f32_e32 v180, v106
	v_exp_f32_e32 v181, v107
	v_mfma_f32_32x32x16_bf16 v[32:47], v[120:123], v[172:175], v[32:47]
	ds_read_b128 v[104:107], v236 offset:12288
	v_exp_f32_e32 v182, v108
	v_exp_f32_e32 v183, v109
	v_exp_f32_e32 v184, v110
	v_exp_f32_e32 v185, v111
	v_cvt_pk_bf16_f32 v108, v144, v145
	v_cvt_pk_bf16_f32 v109, v146, v147
	v_cvt_pk_bf16_f32 v110, v148, v149
	v_cvt_pk_bf16_f32 v111, v150, v151
	s_nop 1
	v_mfma_f32_32x32x16_bf16 v[80:95], v[124:127], v[108:111], v[80:95]
	ds_read_b128 v[112:115], v237
	v_cvt_pk_bf16_f32 v116, v152, v153
	v_cvt_pk_bf16_f32 v117, v154, v155
	v_cvt_pk_bf16_f32 v118, v156, v157
	v_cvt_pk_bf16_f32 v119, v158, v159
	v_mfma_f32_32x32x16_bf16 v[64:79], v[96:99], v[108:111], v[64:79]
	ds_read_b128 v[120:123], v237 offset:4096
	v_pk_add_f32 v[126:127], v[150:151], v[146:147]
	v_pk_add_f32 v[124:125], v[148:149], v[144:145]
	s_waitcnt lgkmcnt(0)
	v_mfma_f32_32x32x16_bf16 v[16:31], v[100:103], v[108:111], v[16:31]
	ds_read_b128 v[132:135], v237 offset:8192
	v_add_f32_e64 v98, v154, v126
	v_add_f32_e64 v99, v155, v127
	v_add_f32_e64 v96, v152, v124
	v_add_f32_e64 v97, v153, v125
	v_pk_add_f32 v[98:99], v[158:159], v[98:99]
	v_pk_add_f32 v[96:97], v[156:157], v[96:97]
	v_mfma_f32_32x32x16_bf16 v[0:15], v[104:107], v[108:111], v[0:15]
	ds_read_b128 v[100:103], v237 offset:12288
	v_mfma_f32_32x32x16_bf16 v[80:95], v[112:115], v[116:119], v[80:95]
	ds_read_b128 v[104:107], v238
	v_cvt_pk_bf16_f32 v108, v136, v137
	v_cvt_pk_bf16_f32 v109, v138, v139
	v_cvt_pk_bf16_f32 v110, v140, v141
	v_cvt_pk_bf16_f32 v111, v142, v143
	v_mfma_f32_32x32x16_bf16 v[64:79], v[120:123], v[116:119], v[64:79]
	ds_read_b128 v[112:115], v238 offset:4096
	v_add_f32_e64 v98, v138, v98
	v_add_f32_e64 v99, v139, v99
	v_add_f32_e64 v96, v136, v96
	v_add_f32_e64 v97, v137, v97
	v_pk_add_f32 v[98:99], v[142:143], v[98:99]
	v_pk_add_f32 v[96:97], v[140:141], v[96:97]
	s_waitcnt lgkmcnt(0)
	v_mfma_f32_32x32x16_bf16 v[16:31], v[132:135], v[116:119], v[16:31]
	ds_read_b128 v[120:123], v238 offset:8192
	v_add_f32_e64 v98, v180, v98
	v_add_f32_e64 v99, v181, v99
	v_add_f32_e64 v96, v178, v96
	v_add_f32_e64 v97, v179, v97
	v_pk_add_f32 v[98:99], v[184:185], v[98:99]
	v_pk_add_f32 v[96:97], v[182:183], v[96:97]
	v_mfma_f32_32x32x16_bf16 v[0:15], v[100:103], v[116:119], v[0:15]
	ds_read_b128 v[124:127], v238 offset:12288
	v_mfma_f32_32x32x16_bf16 v[80:95], v[104:107], v[108:111], v[80:95]
	ds_read_b128 v[100:103], v239
	v_cvt_pk_bf16_f32 v116, v178, v179
	v_cvt_pk_bf16_f32 v117, v180, v181
	v_cvt_pk_bf16_f32 v118, v182, v183
	v_cvt_pk_bf16_f32 v119, v184, v185
	v_mfma_f32_32x32x16_bf16 v[64:79], v[112:115], v[108:111], v[64:79]
	ds_read_b128 v[104:107], v239 offset:4096
	s_waitcnt lgkmcnt(0)
	v_mfma_f32_32x32x16_bf16 v[16:31], v[120:123], v[108:111], v[16:31]
	ds_read_b128 v[112:115], v239 offset:8192
	v_mfma_f32_32x32x16_bf16 v[0:15], v[124:127], v[108:111], v[0:15]
	ds_read_b128 v[120:123], v239 offset:12288
	v_mfma_f32_32x32x16_bf16 v[80:95], v[100:103], v[116:119], v[80:95]
	v_mfma_f32_32x32x16_bf16 v[64:79], v[104:107], v[116:119], v[64:79]
	s_waitcnt lgkmcnt(0)
	v_mfma_f32_32x32x16_bf16 v[16:31], v[112:115], v[116:119], v[16:31]
	v_mfma_f32_32x32x16_bf16 v[0:15], v[120:123], v[116:119], v[0:15]
	s_waitcnt vmcnt(4) lgkmcnt(0)
	v_add_f32_e32 v100, v128, v129
	v_add_f32_e32 v101, v130, v131
	v_add_f32_e32 v100, v100, v101
	v_add_f32_e32 v96, v96, v97
	v_add_f32_e32 v97, v98, v99
	s_barrier
	v_add_f32_e32 v100, v177, v100
	v_add_f32_e32 v96, v96, v97
	v_add_f32_e32 v177, v100, v96
	s_add_u32 s98, s98, 0x30000
	s_addc_u32 s99, s99, 0
	s_add_u32 s100, s100, 0x100
	s_addc_u32 s101, s101, 0
	s_add_i32 s46, s58, 0
	s_mov_b32 m0, s46
	s_nop 0
	global_load_lds_dwordx4 v198, s[98:99]
	s_add_i32 m0, s46, 0x400
	s_nop 0
	global_load_lds_dwordx4 v194, s[98:99]
	s_add_i32 s48, s58, 0
	s_add_i32 m0, s48, 0xc000
	s_nop 0
	global_load_lds_dwordx4 v196, s[100:101]
	s_add_i32 m0, s48, 0xc400
	s_nop 0
	global_load_lds_dwordx4 v192, s[100:101]
	ds_read_b128 v[96:99], v205 offset:16384
	ds_read_b128 v[100:103], v205 offset:24576
	v_exp_f32_e32 v140, v48
	v_exp_f32_e32 v141, v49
	v_exp_f32_e32 v142, v50
	v_exp_f32_e32 v143, v51
	s_waitcnt lgkmcnt(0)
	v_mfma_f32_32x32x16_bf16 v[112:127], v[96:99], v[160:163], 0
	ds_read_b128 v[128:131], v211 offset:16384
	ds_read_b128 v[132:135], v211 offset:24576
	ds_read_b128 v[136:139], v212 offset:16384
	ds_read_b128 v[48:51], v212 offset:24576
	v_mfma_f32_32x32x16_bf16 v[96:111], v[100:103], v[160:163], 0
	v_exp_f32_e32 v144, v52
	v_exp_f32_e32 v145, v53
	v_exp_f32_e32 v146, v54
	v_exp_f32_e32 v147, v55
	s_waitcnt lgkmcnt(0)
	v_mfma_f32_32x32x16_bf16 v[112:127], v[128:131], v[164:167], v[112:127]
	ds_read_b128 v[52:55], v213 offset:16384
	v_exp_f32_e32 v148, v56
	v_exp_f32_e32 v149, v57
	v_exp_f32_e32 v150, v58
	v_exp_f32_e32 v151, v59
	v_mfma_f32_32x32x16_bf16 v[96:111], v[132:135], v[164:167], v[96:111]
	ds_read_b128 v[56:59], v213 offset:24576
	v_exp_f32_e32 v128, v60
	v_exp_f32_e32 v129, v61
	v_exp_f32_e32 v130, v62
	v_exp_f32_e32 v131, v63
	v_mfma_f32_32x32x16_bf16 v[112:127], v[136:139], v[168:171], v[112:127]
	ds_read_b128 v[60:63], v236 offset:16384
	v_exp_f32_e32 v132, v32
	v_exp_f32_e32 v133, v33
	v_exp_f32_e32 v134, v34
	v_exp_f32_e32 v135, v35
	v_mfma_f32_32x32x16_bf16 v[96:111], v[48:51], v[168:171], v[96:111]
	ds_read_b128 v[32:35], v236 offset:20480
	v_exp_f32_e32 v136, v36
	v_exp_f32_e32 v137, v37
	v_exp_f32_e32 v138, v38
	v_exp_f32_e32 v139, v39
	s_waitcnt lgkmcnt(0)
	v_mfma_f32_32x32x16_bf16 v[112:127], v[52:55], v[172:175], v[112:127]
	ds_read_b128 v[36:39], v236 offset:24576
	v_exp_f32_e32 v152, v40
	v_exp_f32_e32 v153, v41
	v_exp_f32_e32 v154, v42
	v_exp_f32_e32 v155, v43
	v_mfma_f32_32x32x16_bf16 v[96:111], v[56:59], v[172:175], v[96:111]
	ds_read_b128 v[40:43], v236 offset:28672
	v_exp_f32_e32 v156, v44
	v_exp_f32_e32 v157, v45
	v_exp_f32_e32 v158, v46
	v_exp_f32_e32 v159, v47
	v_cvt_pk_bf16_f32 v44, v140, v141
	v_cvt_pk_bf16_f32 v45, v142, v143
	v_cvt_pk_bf16_f32 v46, v144, v145
	v_cvt_pk_bf16_f32 v47, v146, v147
	s_nop 1
	v_mfma_f32_32x32x16_bf16 v[80:95], v[60:63], v[44:47], v[80:95]
	ds_read_b128 v[48:51], v237 offset:16384
	v_cvt_pk_bf16_f32 v52, v148, v149
	v_cvt_pk_bf16_f32 v53, v150, v151
	v_cvt_pk_bf16_f32 v54, v128, v129
	v_cvt_pk_bf16_f32 v55, v130, v131
	v_mfma_f32_32x32x16_bf16 v[64:79], v[32:35], v[44:47], v[64:79]
	ds_read_b128 v[56:59], v237 offset:20480
	v_pk_add_f32 v[62:63], v[146:147], v[142:143]
	v_pk_add_f32 v[60:61], v[144:145], v[140:141]
	s_waitcnt lgkmcnt(0)
	v_mfma_f32_32x32x16_bf16 v[16:31], v[36:39], v[44:47], v[16:31]
	ds_read_b128 v[32:35], v237 offset:24576
	v_add_f32_e64 v62, v150, v62
	v_add_f32_e64 v63, v151, v63
	v_add_f32_e64 v60, v148, v60
	v_add_f32_e64 v61, v149, v61
	v_pk_add_f32 v[62:63], v[130:131], v[62:63]
	v_pk_add_f32 v[60:61], v[128:129], v[60:61]
	v_mfma_f32_32x32x16_bf16 v[0:15], v[40:43], v[44:47], v[0:15]
	ds_read_b128 v[36:39], v237 offset:28672
	v_mfma_f32_32x32x16_bf16 v[80:95], v[48:51], v[52:55], v[80:95]
	ds_read_b128 v[40:43], v238 offset:16384
	v_cvt_pk_bf16_f32 v44, v132, v133
	v_cvt_pk_bf16_f32 v45, v134, v135
	v_cvt_pk_bf16_f32 v46, v136, v137
	v_cvt_pk_bf16_f32 v47, v138, v139
	v_mfma_f32_32x32x16_bf16 v[64:79], v[56:59], v[52:55], v[64:79]
	ds_read_b128 v[48:51], v238 offset:20480
	v_add_f32_e64 v62, v134, v62
	v_add_f32_e64 v63, v135, v63
	v_add_f32_e64 v60, v132, v60
	v_add_f32_e64 v61, v133, v61
	v_pk_add_f32 v[62:63], v[138:139], v[62:63]
	v_pk_add_f32 v[60:61], v[136:137], v[60:61]
	s_waitcnt lgkmcnt(0)
	v_mfma_f32_32x32x16_bf16 v[16:31], v[32:35], v[52:55], v[16:31]
	ds_read_b128 v[56:59], v238 offset:24576
	v_add_f32_e64 v62, v154, v62
	v_add_f32_e64 v63, v155, v63
	v_add_f32_e64 v60, v152, v60
	v_add_f32_e64 v61, v153, v61
	v_pk_add_f32 v[130:131], v[158:159], v[62:63]
	v_pk_add_f32 v[128:129], v[156:157], v[60:61]
	v_mfma_f32_32x32x16_bf16 v[0:15], v[36:39], v[52:55], v[0:15]
	ds_read_b128 v[32:35], v238 offset:28672
	v_mfma_f32_32x32x16_bf16 v[80:95], v[40:43], v[44:47], v[80:95]
	ds_read_b128 v[36:39], v239 offset:16384
	v_cvt_pk_bf16_f32 v52, v152, v153
	v_cvt_pk_bf16_f32 v53, v154, v155
	v_cvt_pk_bf16_f32 v54, v156, v157
	v_cvt_pk_bf16_f32 v55, v158, v159
	v_mfma_f32_32x32x16_bf16 v[64:79], v[48:51], v[44:47], v[64:79]
	ds_read_b128 v[40:43], v239 offset:20480
	s_waitcnt lgkmcnt(0)
	v_mfma_f32_32x32x16_bf16 v[16:31], v[56:59], v[44:47], v[16:31]
	ds_read_b128 v[48:51], v239 offset:24576
	v_mfma_f32_32x32x16_bf16 v[0:15], v[32:35], v[44:47], v[0:15]
	ds_read_b128 v[56:59], v239 offset:28672
	v_mfma_f32_32x32x16_bf16 v[80:95], v[36:39], v[52:55], v[80:95]
	v_mfma_f32_32x32x16_bf16 v[64:79], v[40:43], v[52:55], v[64:79]
	s_waitcnt lgkmcnt(0)
	v_mfma_f32_32x32x16_bf16 v[16:31], v[48:51], v[52:55], v[16:31]
	v_mfma_f32_32x32x16_bf16 v[0:15], v[56:59], v[52:55], v[0:15]
	s_waitcnt vmcnt(4) lgkmcnt(0)
	s_barrier
	s_add_u32 s68, s98, 0x18000
	s_addc_u32 s69, s99, 0
	s_add_i32 s49, 0x4000, s57
	s_mov_b32 m0, s49
	s_nop 0
	global_load_lds_dwordx4 v198, s[68:69]
	s_add_i32 m0, s49, 0x400
	s_nop 0
	global_load_lds_dwordx4 v194, s[68:69]
	s_add_u32 s44, s100, 0x80
	s_addc_u32 s45, s101, 0
	s_add_i32 s49, s58, 0x4000
	s_add_i32 m0, s49, 0xc000
	s_nop 0
	global_load_lds_dwordx4 v196, s[44:45]
	s_add_i32 m0, s49, 0xc400
	s_nop 0
	global_load_lds_dwordx4 v192, s[44:45]
	v_exp_f32_e32 v144, v112
	ds_read_b128 v[32:35], v205 offset:32768
	ds_read_b128 v[36:39], v205 offset:40960
	v_exp_f32_e32 v145, v113
	v_exp_f32_e32 v146, v114
	v_exp_f32_e32 v147, v115
	s_waitcnt lgkmcnt(0)
	v_mfma_f32_32x32x16_bf16 v[48:63], v[32:35], v[160:163], 0
	ds_read_b128 v[132:135], v211 offset:32768
	ds_read_b128 v[136:139], v211 offset:40960
	ds_read_b128 v[140:143], v212 offset:32768
	ds_read_b128 v[112:115], v212 offset:40960
	v_mfma_f32_32x32x16_bf16 v[32:47], v[36:39], v[160:163], 0
	v_exp_f32_e32 v148, v116
	v_exp_f32_e32 v149, v117
	v_exp_f32_e32 v150, v118
	v_exp_f32_e32 v151, v119
	s_waitcnt lgkmcnt(0)
	v_mfma_f32_32x32x16_bf16 v[48:63], v[132:135], v[164:167], v[48:63]
	ds_read_b128 v[116:119], v213 offset:32768
	v_exp_f32_e32 v152, v120
	v_exp_f32_e32 v153, v121
	v_exp_f32_e32 v154, v122
	v_exp_f32_e32 v155, v123
	v_mfma_f32_32x32x16_bf16 v[32:47], v[136:139], v[164:167], v[32:47]
	ds_read_b128 v[120:123], v213 offset:40960
	v_exp_f32_e32 v156, v124
	v_exp_f32_e32 v157, v125
	v_exp_f32_e32 v158, v126
	v_exp_f32_e32 v159, v127
	v_mfma_f32_32x32x16_bf16 v[48:63], v[140:143], v[168:171], v[48:63]
	ds_read_b128 v[124:127], v236 offset:32768
	v_exp_f32_e32 v136, v96
	v_exp_f32_e32 v137, v97
	v_exp_f32_e32 v138, v98
	v_exp_f32_e32 v139, v99
	v_mfma_f32_32x32x16_bf16 v[32:47], v[112:115], v[168:171], v[32:47]
	ds_read_b128 v[96:99], v236 offset:36864
	v_exp_f32_e32 v140, v100
	v_exp_f32_e32 v141, v101
	v_exp_f32_e32 v142, v102
	v_exp_f32_e32 v143, v103
	s_waitcnt lgkmcnt(0)
	v_mfma_f32_32x32x16_bf16 v[48:63], v[116:119], v[172:175], v[48:63]
	ds_read_b128 v[100:103], v236 offset:40960
	v_exp_f32_e32 v178, v104
	v_exp_f32_e32 v179, v105
	v_exp_f32_e32 v180, v106
	v_exp_f32_e32 v181, v107
	v_mfma_f32_32x32x16_bf16 v[32:47], v[120:123], v[172:175], v[32:47]
	ds_read_b128 v[104:107], v236 offset:45056
	v_exp_f32_e32 v182, v108
	v_exp_f32_e32 v183, v109
	v_exp_f32_e32 v184, v110
	v_exp_f32_e32 v185, v111
	v_cvt_pk_bf16_f32 v108, v144, v145
	v_cvt_pk_bf16_f32 v109, v146, v147
	v_cvt_pk_bf16_f32 v110, v148, v149
	v_cvt_pk_bf16_f32 v111, v150, v151
	s_nop 1
	v_mfma_f32_32x32x16_bf16 v[80:95], v[124:127], v[108:111], v[80:95]
	ds_read_b128 v[112:115], v237 offset:32768
	v_cvt_pk_bf16_f32 v116, v152, v153
	v_cvt_pk_bf16_f32 v117, v154, v155
	v_cvt_pk_bf16_f32 v118, v156, v157
	v_cvt_pk_bf16_f32 v119, v158, v159
	v_mfma_f32_32x32x16_bf16 v[64:79], v[96:99], v[108:111], v[64:79]
	ds_read_b128 v[120:123], v237 offset:36864
	v_pk_add_f32 v[126:127], v[150:151], v[146:147]
	v_pk_add_f32 v[124:125], v[148:149], v[144:145]
	s_waitcnt lgkmcnt(0)
	v_mfma_f32_32x32x16_bf16 v[16:31], v[100:103], v[108:111], v[16:31]
	ds_read_b128 v[132:135], v237 offset:40960
	v_add_f32_e64 v98, v154, v126
	v_add_f32_e64 v99, v155, v127
	v_add_f32_e64 v96, v152, v124
	v_add_f32_e64 v97, v153, v125
	v_pk_add_f32 v[98:99], v[158:159], v[98:99]
	v_pk_add_f32 v[96:97], v[156:157], v[96:97]
	v_mfma_f32_32x32x16_bf16 v[0:15], v[104:107], v[108:111], v[0:15]
	ds_read_b128 v[100:103], v237 offset:45056
	v_mfma_f32_32x32x16_bf16 v[80:95], v[112:115], v[116:119], v[80:95]
	ds_read_b128 v[104:107], v238 offset:32768
	v_cvt_pk_bf16_f32 v108, v136, v137
	v_cvt_pk_bf16_f32 v109, v138, v139
	v_cvt_pk_bf16_f32 v110, v140, v141
	v_cvt_pk_bf16_f32 v111, v142, v143
	v_mfma_f32_32x32x16_bf16 v[64:79], v[120:123], v[116:119], v[64:79]
	ds_read_b128 v[112:115], v238 offset:36864
	v_add_f32_e64 v98, v138, v98
	v_add_f32_e64 v99, v139, v99
	v_add_f32_e64 v96, v136, v96
	v_add_f32_e64 v97, v137, v97
	v_pk_add_f32 v[98:99], v[142:143], v[98:99]
	v_pk_add_f32 v[96:97], v[140:141], v[96:97]
	s_waitcnt lgkmcnt(0)
	v_mfma_f32_32x32x16_bf16 v[16:31], v[132:135], v[116:119], v[16:31]
	ds_read_b128 v[120:123], v238 offset:40960
	v_add_f32_e64 v98, v180, v98
	v_add_f32_e64 v99, v181, v99
	v_add_f32_e64 v96, v178, v96
	v_add_f32_e64 v97, v179, v97
	v_pk_add_f32 v[98:99], v[184:185], v[98:99]
	v_pk_add_f32 v[96:97], v[182:183], v[96:97]
	v_mfma_f32_32x32x16_bf16 v[0:15], v[100:103], v[116:119], v[0:15]
	ds_read_b128 v[124:127], v238 offset:45056
	v_mfma_f32_32x32x16_bf16 v[80:95], v[104:107], v[108:111], v[80:95]
	ds_read_b128 v[100:103], v239 offset:32768
	v_cvt_pk_bf16_f32 v116, v178, v179
	v_cvt_pk_bf16_f32 v117, v180, v181
	v_cvt_pk_bf16_f32 v118, v182, v183
	v_cvt_pk_bf16_f32 v119, v184, v185
	v_mfma_f32_32x32x16_bf16 v[64:79], v[112:115], v[108:111], v[64:79]
	ds_read_b128 v[104:107], v239 offset:36864
	s_waitcnt lgkmcnt(0)
	v_mfma_f32_32x32x16_bf16 v[16:31], v[120:123], v[108:111], v[16:31]
	ds_read_b128 v[112:115], v239 offset:40960
	v_mfma_f32_32x32x16_bf16 v[0:15], v[124:127], v[108:111], v[0:15]
	ds_read_b128 v[120:123], v239 offset:45056
	v_mfma_f32_32x32x16_bf16 v[80:95], v[100:103], v[116:119], v[80:95]
	v_mfma_f32_32x32x16_bf16 v[64:79], v[104:107], v[116:119], v[64:79]
	s_waitcnt lgkmcnt(0)
	v_mfma_f32_32x32x16_bf16 v[16:31], v[112:115], v[116:119], v[16:31]
	v_mfma_f32_32x32x16_bf16 v[0:15], v[120:123], v[116:119], v[0:15]
	s_waitcnt vmcnt(4) lgkmcnt(0)
	v_add_f32_e32 v100, v128, v129
	v_add_f32_e32 v101, v130, v131
	v_add_f32_e32 v100, v100, v101
	v_add_f32_e32 v96, v96, v97
	v_add_f32_e32 v97, v98, v99
	s_barrier
	v_add_f32_e32 v100, v177, v100
	v_add_f32_e32 v96, v96, v97
	v_add_f32_e32 v177, v100, v96
	s_add_u32 s98, s98, 0x30000
	s_addc_u32 s99, s99, 0
	s_add_u32 s100, s100, 0x100
	s_addc_u32 s101, s101, 0
	s_add_i32 s46, s58, 0x8000
	s_mov_b32 m0, s46
	s_nop 0
	global_load_lds_dwordx4 v198, s[98:99]
	s_add_i32 m0, s46, 0x400
	s_nop 0
	global_load_lds_dwordx4 v194, s[98:99]
	s_add_i32 s48, s58, 0x8000
	s_add_i32 m0, s48, 0xc000
	s_nop 0
	global_load_lds_dwordx4 v196, s[100:101]
	s_add_i32 m0, s48, 0xc400
	s_nop 0
	global_load_lds_dwordx4 v192, s[100:101]
	ds_read_b128 v[96:99], v205
	ds_read_b128 v[100:103], v205 offset:8192
	v_exp_f32_e32 v140, v48
	v_exp_f32_e32 v141, v49
	v_exp_f32_e32 v142, v50
	v_exp_f32_e32 v143, v51
	s_waitcnt lgkmcnt(0)
	v_mfma_f32_32x32x16_bf16 v[112:127], v[96:99], v[160:163], 0
	ds_read_b128 v[128:131], v211
	ds_read_b128 v[132:135], v211 offset:8192
	ds_read_b128 v[136:139], v212
	ds_read_b128 v[48:51], v212 offset:8192
	v_mfma_f32_32x32x16_bf16 v[96:111], v[100:103], v[160:163], 0
	v_exp_f32_e32 v144, v52
	v_exp_f32_e32 v145, v53
	v_exp_f32_e32 v146, v54
	v_exp_f32_e32 v147, v55
	s_waitcnt lgkmcnt(0)
	v_mfma_f32_32x32x16_bf16 v[112:127], v[128:131], v[164:167], v[112:127]
	ds_read_b128 v[52:55], v213
	v_exp_f32_e32 v148, v56
	v_exp_f32_e32 v149, v57
	v_exp_f32_e32 v150, v58
	v_exp_f32_e32 v151, v59
	v_mfma_f32_32x32x16_bf16 v[96:111], v[132:135], v[164:167], v[96:111]
	ds_read_b128 v[56:59], v213 offset:8192
	v_exp_f32_e32 v128, v60
	v_exp_f32_e32 v129, v61
	v_exp_f32_e32 v130, v62
	v_exp_f32_e32 v131, v63
	v_mfma_f32_32x32x16_bf16 v[112:127], v[136:139], v[168:171], v[112:127]
	ds_read_b128 v[60:63], v206 offset:49152
	v_exp_f32_e32 v132, v32
	v_exp_f32_e32 v133, v33
	v_exp_f32_e32 v134, v34
	v_exp_f32_e32 v135, v35
	v_mfma_f32_32x32x16_bf16 v[96:111], v[48:51], v[168:171], v[96:111]
	ds_read_b128 v[32:35], v206 offset:53248
	v_exp_f32_e32 v136, v36
	v_exp_f32_e32 v137, v37
	v_exp_f32_e32 v138, v38
	v_exp_f32_e32 v139, v39
	s_waitcnt lgkmcnt(0)
	v_mfma_f32_32x32x16_bf16 v[112:127], v[52:55], v[172:175], v[112:127]
	ds_read_b128 v[36:39], v206 offset:57344
	v_exp_f32_e32 v152, v40
	v_exp_f32_e32 v153, v41
	v_exp_f32_e32 v154, v42
	v_exp_f32_e32 v155, v43
	v_mfma_f32_32x32x16_bf16 v[96:111], v[56:59], v[172:175], v[96:111]
	ds_read_b128 v[40:43], v206 offset:61440
	v_exp_f32_e32 v156, v44
	v_exp_f32_e32 v157, v45
	v_exp_f32_e32 v158, v46
	v_exp_f32_e32 v159, v47
	v_cvt_pk_bf16_f32 v44, v140, v141
	v_cvt_pk_bf16_f32 v45, v142, v143
	v_cvt_pk_bf16_f32 v46, v144, v145
	v_cvt_pk_bf16_f32 v47, v146, v147
	s_nop 1
	v_mfma_f32_32x32x16_bf16 v[80:95], v[60:63], v[44:47], v[80:95]
	ds_read_b128 v[48:51], v207 offset:49152
	v_cvt_pk_bf16_f32 v52, v148, v149
	v_cvt_pk_bf16_f32 v53, v150, v151
	v_cvt_pk_bf16_f32 v54, v128, v129
	v_cvt_pk_bf16_f32 v55, v130, v131
	v_mfma_f32_32x32x16_bf16 v[64:79], v[32:35], v[44:47], v[64:79]
	ds_read_b128 v[56:59], v207 offset:53248
	v_pk_add_f32 v[62:63], v[146:147], v[142:143]
	v_pk_add_f32 v[60:61], v[144:145], v[140:141]
	s_waitcnt lgkmcnt(0)
	v_mfma_f32_32x32x16_bf16 v[16:31], v[36:39], v[44:47], v[16:31]
	ds_read_b128 v[32:35], v207 offset:57344
	v_add_f32_e64 v62, v150, v62
	v_add_f32_e64 v63, v151, v63
	v_add_f32_e64 v60, v148, v60
	v_add_f32_e64 v61, v149, v61
	v_pk_add_f32 v[62:63], v[130:131], v[62:63]
	v_pk_add_f32 v[60:61], v[128:129], v[60:61]
	v_mfma_f32_32x32x16_bf16 v[0:15], v[40:43], v[44:47], v[0:15]
	ds_read_b128 v[36:39], v207 offset:61440
	v_mfma_f32_32x32x16_bf16 v[80:95], v[48:51], v[52:55], v[80:95]
	ds_read_b128 v[40:43], v208 offset:49152
	v_cvt_pk_bf16_f32 v44, v132, v133
	v_cvt_pk_bf16_f32 v45, v134, v135
	v_cvt_pk_bf16_f32 v46, v136, v137
	v_cvt_pk_bf16_f32 v47, v138, v139
	v_mfma_f32_32x32x16_bf16 v[64:79], v[56:59], v[52:55], v[64:79]
	ds_read_b128 v[48:51], v208 offset:53248
	v_add_f32_e64 v62, v134, v62
	v_add_f32_e64 v63, v135, v63
	v_add_f32_e64 v60, v132, v60
	v_add_f32_e64 v61, v133, v61
	v_pk_add_f32 v[62:63], v[138:139], v[62:63]
	v_pk_add_f32 v[60:61], v[136:137], v[60:61]
	s_waitcnt lgkmcnt(0)
	v_mfma_f32_32x32x16_bf16 v[16:31], v[32:35], v[52:55], v[16:31]
	ds_read_b128 v[56:59], v208 offset:57344
	v_add_f32_e64 v62, v154, v62
	v_add_f32_e64 v63, v155, v63
	v_add_f32_e64 v60, v152, v60
	v_add_f32_e64 v61, v153, v61
	v_pk_add_f32 v[130:131], v[158:159], v[62:63]
	v_pk_add_f32 v[128:129], v[156:157], v[60:61]
	v_mfma_f32_32x32x16_bf16 v[0:15], v[36:39], v[52:55], v[0:15]
	ds_read_b128 v[32:35], v208 offset:61440
	v_mfma_f32_32x32x16_bf16 v[80:95], v[40:43], v[44:47], v[80:95]
	ds_read_b128 v[36:39], v209 offset:49152
	v_cvt_pk_bf16_f32 v52, v152, v153
	v_cvt_pk_bf16_f32 v53, v154, v155
	v_cvt_pk_bf16_f32 v54, v156, v157
	v_cvt_pk_bf16_f32 v55, v158, v159
	v_mfma_f32_32x32x16_bf16 v[64:79], v[48:51], v[44:47], v[64:79]
	ds_read_b128 v[40:43], v209 offset:53248
	s_waitcnt lgkmcnt(0)
	v_mfma_f32_32x32x16_bf16 v[16:31], v[56:59], v[44:47], v[16:31]
	ds_read_b128 v[48:51], v209 offset:57344
	v_mfma_f32_32x32x16_bf16 v[0:15], v[32:35], v[44:47], v[0:15]
	ds_read_b128 v[56:59], v209 offset:61440
	v_mfma_f32_32x32x16_bf16 v[80:95], v[36:39], v[52:55], v[80:95]
	v_mfma_f32_32x32x16_bf16 v[64:79], v[40:43], v[52:55], v[64:79]
	s_waitcnt lgkmcnt(0)
	v_mfma_f32_32x32x16_bf16 v[16:31], v[48:51], v[52:55], v[16:31]
	v_mfma_f32_32x32x16_bf16 v[0:15], v[56:59], v[52:55], v[0:15]
	s_waitcnt vmcnt(4) lgkmcnt(0)
	s_barrier
	s_add_u32 s68, s98, 0x18000
	s_addc_u32 s69, s99, 0
	s_add_i32 s49, 0, s57
	s_mov_b32 m0, s49
	s_nop 0
	global_load_lds_dwordx4 v198, s[68:69]
	s_add_i32 m0, s49, 0x400
	s_nop 0
	global_load_lds_dwordx4 v194, s[68:69]
	s_add_u32 s44, s100, 0x80
	s_addc_u32 s45, s101, 0
	s_add_i32 s49, s58, 0xc000
	s_add_i32 m0, s49, 0xc000
	s_nop 0
	global_load_lds_dwordx4 v196, s[44:45]
	s_add_i32 m0, s49, 0xc400
	s_nop 0
	global_load_lds_dwordx4 v192, s[44:45]
	v_exp_f32_e32 v144, v112
	ds_read_b128 v[32:35], v205 offset:16384
	ds_read_b128 v[36:39], v205 offset:24576
	v_exp_f32_e32 v145, v113
	v_exp_f32_e32 v146, v114
	v_exp_f32_e32 v147, v115
	s_waitcnt lgkmcnt(0)
	v_mfma_f32_32x32x16_bf16 v[48:63], v[32:35], v[160:163], 0
	ds_read_b128 v[132:135], v211 offset:16384
	ds_read_b128 v[136:139], v211 offset:24576
	ds_read_b128 v[140:143], v212 offset:16384
	ds_read_b128 v[112:115], v212 offset:24576
	v_mfma_f32_32x32x16_bf16 v[32:47], v[36:39], v[160:163], 0
	v_exp_f32_e32 v148, v116
	v_exp_f32_e32 v149, v117
	v_exp_f32_e32 v150, v118
	v_exp_f32_e32 v151, v119
	s_waitcnt lgkmcnt(0)
	v_mfma_f32_32x32x16_bf16 v[48:63], v[132:135], v[164:167], v[48:63]
	ds_read_b128 v[116:119], v213 offset:16384
	v_exp_f32_e32 v152, v120
	v_exp_f32_e32 v153, v121
	v_exp_f32_e32 v154, v122
	v_exp_f32_e32 v155, v123
	v_mfma_f32_32x32x16_bf16 v[32:47], v[136:139], v[164:167], v[32:47]
	ds_read_b128 v[120:123], v213 offset:24576
	v_exp_f32_e32 v156, v124
	v_exp_f32_e32 v157, v125
	v_exp_f32_e32 v158, v126
	v_exp_f32_e32 v159, v127
	v_mfma_f32_32x32x16_bf16 v[48:63], v[140:143], v[168:171], v[48:63]
	ds_read_b128 v[124:127], v236
	v_exp_f32_e32 v136, v96
	v_exp_f32_e32 v137, v97
	v_exp_f32_e32 v138, v98
	v_exp_f32_e32 v139, v99
	v_mfma_f32_32x32x16_bf16 v[32:47], v[112:115], v[168:171], v[32:47]
	ds_read_b128 v[96:99], v236 offset:4096
	v_exp_f32_e32 v140, v100
	v_exp_f32_e32 v141, v101
	v_exp_f32_e32 v142, v102
	v_exp_f32_e32 v143, v103
	s_waitcnt lgkmcnt(0)
	v_mfma_f32_32x32x16_bf16 v[48:63], v[116:119], v[172:175], v[48:63]
	ds_read_b128 v[100:103], v236 offset:8192
	v_exp_f32_e32 v178, v104
	v_exp_f32_e32 v179, v105
	v_exp_f32_e32 v180, v106
	v_exp_f32_e32 v181, v107
	v_mfma_f32_32x32x16_bf16 v[32:47], v[120:123], v[172:175], v[32:47]
	ds_read_b128 v[104:107], v236 offset:12288
	v_exp_f32_e32 v182, v108
	v_exp_f32_e32 v183, v109
	v_exp_f32_e32 v184, v110
	v_exp_f32_e32 v185, v111
	v_cvt_pk_bf16_f32 v108, v144, v145
	v_cvt_pk_bf16_f32 v109, v146, v147
	v_cvt_pk_bf16_f32 v110, v148, v149
	v_cvt_pk_bf16_f32 v111, v150, v151
	s_nop 1
	v_mfma_f32_32x32x16_bf16 v[80:95], v[124:127], v[108:111], v[80:95]
	ds_read_b128 v[112:115], v237
	v_cvt_pk_bf16_f32 v116, v152, v153
	v_cvt_pk_bf16_f32 v117, v154, v155
	v_cvt_pk_bf16_f32 v118, v156, v157
	v_cvt_pk_bf16_f32 v119, v158, v159
	v_mfma_f32_32x32x16_bf16 v[64:79], v[96:99], v[108:111], v[64:79]
	ds_read_b128 v[120:123], v237 offset:4096
	v_pk_add_f32 v[126:127], v[150:151], v[146:147]
	v_pk_add_f32 v[124:125], v[148:149], v[144:145]
	s_waitcnt lgkmcnt(0)
	v_mfma_f32_32x32x16_bf16 v[16:31], v[100:103], v[108:111], v[16:31]
	ds_read_b128 v[132:135], v237 offset:8192
	v_add_f32_e64 v98, v154, v126
	v_add_f32_e64 v99, v155, v127
	v_add_f32_e64 v96, v152, v124
	v_add_f32_e64 v97, v153, v125
	v_pk_add_f32 v[98:99], v[158:159], v[98:99]
	v_pk_add_f32 v[96:97], v[156:157], v[96:97]
	v_mfma_f32_32x32x16_bf16 v[0:15], v[104:107], v[108:111], v[0:15]
	ds_read_b128 v[100:103], v237 offset:12288
	v_mfma_f32_32x32x16_bf16 v[80:95], v[112:115], v[116:119], v[80:95]
	ds_read_b128 v[104:107], v238
	v_cvt_pk_bf16_f32 v108, v136, v137
	v_cvt_pk_bf16_f32 v109, v138, v139
	v_cvt_pk_bf16_f32 v110, v140, v141
	v_cvt_pk_bf16_f32 v111, v142, v143
	v_mfma_f32_32x32x16_bf16 v[64:79], v[120:123], v[116:119], v[64:79]
	ds_read_b128 v[112:115], v238 offset:4096
	v_add_f32_e64 v98, v138, v98
	v_add_f32_e64 v99, v139, v99
	v_add_f32_e64 v96, v136, v96
	v_add_f32_e64 v97, v137, v97
	v_pk_add_f32 v[98:99], v[142:143], v[98:99]
	v_pk_add_f32 v[96:97], v[140:141], v[96:97]
	s_waitcnt lgkmcnt(0)
	v_mfma_f32_32x32x16_bf16 v[16:31], v[132:135], v[116:119], v[16:31]
	ds_read_b128 v[120:123], v238 offset:8192
	v_add_f32_e64 v98, v180, v98
	v_add_f32_e64 v99, v181, v99
	v_add_f32_e64 v96, v178, v96
	v_add_f32_e64 v97, v179, v97
	v_pk_add_f32 v[98:99], v[184:185], v[98:99]
	v_pk_add_f32 v[96:97], v[182:183], v[96:97]
	v_mfma_f32_32x32x16_bf16 v[0:15], v[100:103], v[116:119], v[0:15]
	ds_read_b128 v[124:127], v238 offset:12288
	v_mfma_f32_32x32x16_bf16 v[80:95], v[104:107], v[108:111], v[80:95]
	ds_read_b128 v[100:103], v239
	v_cvt_pk_bf16_f32 v116, v178, v179
	v_cvt_pk_bf16_f32 v117, v180, v181
	v_cvt_pk_bf16_f32 v118, v182, v183
	v_cvt_pk_bf16_f32 v119, v184, v185
	v_mfma_f32_32x32x16_bf16 v[64:79], v[112:115], v[108:111], v[64:79]
	ds_read_b128 v[104:107], v239 offset:4096
	s_waitcnt lgkmcnt(0)
	v_mfma_f32_32x32x16_bf16 v[16:31], v[120:123], v[108:111], v[16:31]
	ds_read_b128 v[112:115], v239 offset:8192
	v_mfma_f32_32x32x16_bf16 v[0:15], v[124:127], v[108:111], v[0:15]
	ds_read_b128 v[120:123], v239 offset:12288
	v_mfma_f32_32x32x16_bf16 v[80:95], v[100:103], v[116:119], v[80:95]
	v_mfma_f32_32x32x16_bf16 v[64:79], v[104:107], v[116:119], v[64:79]
	s_waitcnt lgkmcnt(0)
	v_mfma_f32_32x32x16_bf16 v[16:31], v[112:115], v[116:119], v[16:31]
	v_mfma_f32_32x32x16_bf16 v[0:15], v[120:123], v[116:119], v[0:15]
	s_waitcnt vmcnt(4) lgkmcnt(0)
	v_add_f32_e32 v100, v128, v129
	v_add_f32_e32 v101, v130, v131
	v_add_f32_e32 v100, v100, v101
	v_add_f32_e32 v96, v96, v97
	v_add_f32_e32 v97, v98, v99
	s_barrier
	v_add_f32_e32 v100, v177, v100
	v_add_f32_e32 v96, v96, v97
	v_add_f32_e32 v177, v100, v96
	s_add_u32 s98, s98, 0x30000
	s_addc_u32 s99, s99, 0
	s_add_u32 s100, s100, 0x100
	s_addc_u32 s101, s101, 0
	s_add_i32 s46, s58, 0x4000
	s_mov_b32 m0, s46
	s_nop 0
	global_load_lds_dwordx4 v198, s[98:99]
	s_add_i32 m0, s46, 0x400
	s_nop 0
	global_load_lds_dwordx4 v194, s[98:99]
	s_add_i32 s48, s58, 0
	s_add_i32 m0, s48, 0xc000
	s_nop 0
	global_load_lds_dwordx4 v196, s[100:101]
	s_add_i32 m0, s48, 0xc400
	s_nop 0
	global_load_lds_dwordx4 v192, s[100:101]
	ds_read_b128 v[96:99], v205 offset:32768
	ds_read_b128 v[100:103], v205 offset:40960
	v_exp_f32_e32 v140, v48
	v_exp_f32_e32 v141, v49
	v_exp_f32_e32 v142, v50
	v_exp_f32_e32 v143, v51
	s_waitcnt lgkmcnt(0)
	v_mfma_f32_32x32x16_bf16 v[112:127], v[96:99], v[160:163], 0
	ds_read_b128 v[128:131], v211 offset:32768
	ds_read_b128 v[132:135], v211 offset:40960
	ds_read_b128 v[136:139], v212 offset:32768
	ds_read_b128 v[48:51], v212 offset:40960
	v_mfma_f32_32x32x16_bf16 v[96:111], v[100:103], v[160:163], 0
	v_exp_f32_e32 v144, v52
	v_exp_f32_e32 v145, v53
	v_exp_f32_e32 v146, v54
	v_exp_f32_e32 v147, v55
	s_waitcnt lgkmcnt(0)
	v_mfma_f32_32x32x16_bf16 v[112:127], v[128:131], v[164:167], v[112:127]
	ds_read_b128 v[52:55], v213 offset:32768
	v_exp_f32_e32 v148, v56
	v_exp_f32_e32 v149, v57
	v_exp_f32_e32 v150, v58
	v_exp_f32_e32 v151, v59
	v_mfma_f32_32x32x16_bf16 v[96:111], v[132:135], v[164:167], v[96:111]
	ds_read_b128 v[56:59], v213 offset:40960
	v_exp_f32_e32 v128, v60
	v_exp_f32_e32 v129, v61
	v_exp_f32_e32 v130, v62
	v_exp_f32_e32 v131, v63
	v_mfma_f32_32x32x16_bf16 v[112:127], v[136:139], v[168:171], v[112:127]
	ds_read_b128 v[60:63], v236 offset:16384
	v_exp_f32_e32 v132, v32
	v_exp_f32_e32 v133, v33
	v_exp_f32_e32 v134, v34
	v_exp_f32_e32 v135, v35
	v_mfma_f32_32x32x16_bf16 v[96:111], v[48:51], v[168:171], v[96:111]
	ds_read_b128 v[32:35], v236 offset:20480
	v_exp_f32_e32 v136, v36
	v_exp_f32_e32 v137, v37
	v_exp_f32_e32 v138, v38
	v_exp_f32_e32 v139, v39
	s_waitcnt lgkmcnt(0)
	v_mfma_f32_32x32x16_bf16 v[112:127], v[52:55], v[172:175], v[112:127]
	ds_read_b128 v[36:39], v236 offset:24576
	v_exp_f32_e32 v152, v40
	v_exp_f32_e32 v153, v41
	v_exp_f32_e32 v154, v42
	v_exp_f32_e32 v155, v43
	v_mfma_f32_32x32x16_bf16 v[96:111], v[56:59], v[172:175], v[96:111]
	ds_read_b128 v[40:43], v236 offset:28672
	v_exp_f32_e32 v156, v44
	v_exp_f32_e32 v157, v45
	v_exp_f32_e32 v158, v46
	v_exp_f32_e32 v159, v47
	v_cvt_pk_bf16_f32 v44, v140, v141
	v_cvt_pk_bf16_f32 v45, v142, v143
	v_cvt_pk_bf16_f32 v46, v144, v145
	v_cvt_pk_bf16_f32 v47, v146, v147
	s_nop 1
	v_mfma_f32_32x32x16_bf16 v[80:95], v[60:63], v[44:47], v[80:95]
	ds_read_b128 v[48:51], v237 offset:16384
	v_cvt_pk_bf16_f32 v52, v148, v149
	v_cvt_pk_bf16_f32 v53, v150, v151
	v_cvt_pk_bf16_f32 v54, v128, v129
	v_cvt_pk_bf16_f32 v55, v130, v131
	v_mfma_f32_32x32x16_bf16 v[64:79], v[32:35], v[44:47], v[64:79]
	ds_read_b128 v[56:59], v237 offset:20480
	v_pk_add_f32 v[62:63], v[146:147], v[142:143]
	v_pk_add_f32 v[60:61], v[144:145], v[140:141]
	s_waitcnt lgkmcnt(0)
	v_mfma_f32_32x32x16_bf16 v[16:31], v[36:39], v[44:47], v[16:31]
	ds_read_b128 v[32:35], v237 offset:24576
	v_add_f32_e64 v62, v150, v62
	v_add_f32_e64 v63, v151, v63
	v_add_f32_e64 v60, v148, v60
	v_add_f32_e64 v61, v149, v61
	v_pk_add_f32 v[62:63], v[130:131], v[62:63]
	v_pk_add_f32 v[60:61], v[128:129], v[60:61]
	v_mfma_f32_32x32x16_bf16 v[0:15], v[40:43], v[44:47], v[0:15]
	ds_read_b128 v[36:39], v237 offset:28672
	v_mfma_f32_32x32x16_bf16 v[80:95], v[48:51], v[52:55], v[80:95]
	ds_read_b128 v[40:43], v238 offset:16384
	v_cvt_pk_bf16_f32 v44, v132, v133
	v_cvt_pk_bf16_f32 v45, v134, v135
	v_cvt_pk_bf16_f32 v46, v136, v137
	v_cvt_pk_bf16_f32 v47, v138, v139
	v_mfma_f32_32x32x16_bf16 v[64:79], v[56:59], v[52:55], v[64:79]
	ds_read_b128 v[48:51], v238 offset:20480
	v_add_f32_e64 v62, v134, v62
	v_add_f32_e64 v63, v135, v63
	v_add_f32_e64 v60, v132, v60
	v_add_f32_e64 v61, v133, v61
	v_pk_add_f32 v[62:63], v[138:139], v[62:63]
	v_pk_add_f32 v[60:61], v[136:137], v[60:61]
	s_waitcnt lgkmcnt(0)
	v_mfma_f32_32x32x16_bf16 v[16:31], v[32:35], v[52:55], v[16:31]
	ds_read_b128 v[56:59], v238 offset:24576
	v_add_f32_e64 v62, v154, v62
	v_add_f32_e64 v63, v155, v63
	v_add_f32_e64 v60, v152, v60
	v_add_f32_e64 v61, v153, v61
	v_pk_add_f32 v[130:131], v[158:159], v[62:63]
	v_pk_add_f32 v[128:129], v[156:157], v[60:61]
	v_mfma_f32_32x32x16_bf16 v[0:15], v[36:39], v[52:55], v[0:15]
	ds_read_b128 v[32:35], v238 offset:28672
	v_mfma_f32_32x32x16_bf16 v[80:95], v[40:43], v[44:47], v[80:95]
	ds_read_b128 v[36:39], v239 offset:16384
	v_cvt_pk_bf16_f32 v52, v152, v153
	v_cvt_pk_bf16_f32 v53, v154, v155
	v_cvt_pk_bf16_f32 v54, v156, v157
	v_cvt_pk_bf16_f32 v55, v158, v159
	v_mfma_f32_32x32x16_bf16 v[64:79], v[48:51], v[44:47], v[64:79]
	ds_read_b128 v[40:43], v239 offset:20480
	s_waitcnt lgkmcnt(0)
	v_mfma_f32_32x32x16_bf16 v[16:31], v[56:59], v[44:47], v[16:31]
	ds_read_b128 v[48:51], v239 offset:24576
	v_mfma_f32_32x32x16_bf16 v[0:15], v[32:35], v[44:47], v[0:15]
	ds_read_b128 v[56:59], v239 offset:28672
	v_mfma_f32_32x32x16_bf16 v[80:95], v[36:39], v[52:55], v[80:95]
	v_mfma_f32_32x32x16_bf16 v[64:79], v[40:43], v[52:55], v[64:79]
	s_waitcnt lgkmcnt(0)
	v_mfma_f32_32x32x16_bf16 v[16:31], v[48:51], v[52:55], v[16:31]
	v_mfma_f32_32x32x16_bf16 v[0:15], v[56:59], v[52:55], v[0:15]
	s_waitcnt vmcnt(4) lgkmcnt(0)
	s_barrier
	s_add_u32 s68, s98, 0x18000
	s_addc_u32 s69, s99, 0
	s_add_i32 s49, 0x8000, s57
	s_mov_b32 m0, s49
	s_nop 0
	global_load_lds_dwordx4 v198, s[68:69]
	s_add_i32 m0, s49, 0x400
	s_nop 0
	global_load_lds_dwordx4 v194, s[68:69]
	s_add_u32 s44, s100, 0x80
	s_addc_u32 s45, s101, 0
	s_add_i32 s49, s58, 0x4000
	s_add_i32 m0, s49, 0xc000
	s_nop 0
	global_load_lds_dwordx4 v196, s[44:45]
	s_add_i32 m0, s49, 0xc400
	s_nop 0
	global_load_lds_dwordx4 v192, s[44:45]
	v_exp_f32_e32 v144, v112
	ds_read_b128 v[32:35], v205
	ds_read_b128 v[36:39], v205 offset:8192
	v_exp_f32_e32 v145, v113
	v_exp_f32_e32 v146, v114
	v_exp_f32_e32 v147, v115
	s_waitcnt lgkmcnt(0)
	v_mfma_f32_32x32x16_bf16 v[48:63], v[32:35], v[160:163], 0
	ds_read_b128 v[132:135], v211
	ds_read_b128 v[136:139], v211 offset:8192
	ds_read_b128 v[140:143], v212
	ds_read_b128 v[112:115], v212 offset:8192
	v_mfma_f32_32x32x16_bf16 v[32:47], v[36:39], v[160:163], 0
	v_exp_f32_e32 v148, v116
	v_exp_f32_e32 v149, v117
	v_exp_f32_e32 v150, v118
	v_exp_f32_e32 v151, v119
	s_waitcnt lgkmcnt(0)
	v_mfma_f32_32x32x16_bf16 v[48:63], v[132:135], v[164:167], v[48:63]
	ds_read_b128 v[116:119], v213
	v_exp_f32_e32 v152, v120
	v_exp_f32_e32 v153, v121
	v_exp_f32_e32 v154, v122
	v_exp_f32_e32 v155, v123
	v_mfma_f32_32x32x16_bf16 v[32:47], v[136:139], v[164:167], v[32:47]
	ds_read_b128 v[120:123], v213 offset:8192
	v_exp_f32_e32 v156, v124
	v_exp_f32_e32 v157, v125
	v_exp_f32_e32 v158, v126
	v_exp_f32_e32 v159, v127
	v_mfma_f32_32x32x16_bf16 v[48:63], v[140:143], v[168:171], v[48:63]
	ds_read_b128 v[124:127], v236 offset:32768
	v_exp_f32_e32 v136, v96
	v_exp_f32_e32 v137, v97
	v_exp_f32_e32 v138, v98
	v_exp_f32_e32 v139, v99
	v_mfma_f32_32x32x16_bf16 v[32:47], v[112:115], v[168:171], v[32:47]
	ds_read_b128 v[96:99], v236 offset:36864
	v_exp_f32_e32 v140, v100
	v_exp_f32_e32 v141, v101
	v_exp_f32_e32 v142, v102
	v_exp_f32_e32 v143, v103
	s_waitcnt lgkmcnt(0)
	v_mfma_f32_32x32x16_bf16 v[48:63], v[116:119], v[172:175], v[48:63]
	ds_read_b128 v[100:103], v236 offset:40960
	v_exp_f32_e32 v178, v104
	v_exp_f32_e32 v179, v105
	v_exp_f32_e32 v180, v106
	v_exp_f32_e32 v181, v107
	v_mfma_f32_32x32x16_bf16 v[32:47], v[120:123], v[172:175], v[32:47]
	ds_read_b128 v[104:107], v236 offset:45056
	v_exp_f32_e32 v182, v108
	v_exp_f32_e32 v183, v109
	v_exp_f32_e32 v184, v110
	v_exp_f32_e32 v185, v111
	v_cvt_pk_bf16_f32 v108, v144, v145
	v_cvt_pk_bf16_f32 v109, v146, v147
	v_cvt_pk_bf16_f32 v110, v148, v149
	v_cvt_pk_bf16_f32 v111, v150, v151
	s_nop 1
	v_mfma_f32_32x32x16_bf16 v[80:95], v[124:127], v[108:111], v[80:95]
	ds_read_b128 v[112:115], v237 offset:32768
	v_cvt_pk_bf16_f32 v116, v152, v153
	v_cvt_pk_bf16_f32 v117, v154, v155
	v_cvt_pk_bf16_f32 v118, v156, v157
	v_cvt_pk_bf16_f32 v119, v158, v159
	v_mfma_f32_32x32x16_bf16 v[64:79], v[96:99], v[108:111], v[64:79]
	ds_read_b128 v[120:123], v237 offset:36864
	v_pk_add_f32 v[126:127], v[150:151], v[146:147]
	v_pk_add_f32 v[124:125], v[148:149], v[144:145]
	s_waitcnt lgkmcnt(0)
	v_mfma_f32_32x32x16_bf16 v[16:31], v[100:103], v[108:111], v[16:31]
	ds_read_b128 v[132:135], v237 offset:40960
	v_add_f32_e64 v98, v154, v126
	v_add_f32_e64 v99, v155, v127
	v_add_f32_e64 v96, v152, v124
	v_add_f32_e64 v97, v153, v125
	v_pk_add_f32 v[98:99], v[158:159], v[98:99]
	v_pk_add_f32 v[96:97], v[156:157], v[96:97]
	v_mfma_f32_32x32x16_bf16 v[0:15], v[104:107], v[108:111], v[0:15]
	ds_read_b128 v[100:103], v237 offset:45056
	v_mfma_f32_32x32x16_bf16 v[80:95], v[112:115], v[116:119], v[80:95]
	ds_read_b128 v[104:107], v238 offset:32768
	v_cvt_pk_bf16_f32 v108, v136, v137
	v_cvt_pk_bf16_f32 v109, v138, v139
	v_cvt_pk_bf16_f32 v110, v140, v141
	v_cvt_pk_bf16_f32 v111, v142, v143
	v_mfma_f32_32x32x16_bf16 v[64:79], v[120:123], v[116:119], v[64:79]
	ds_read_b128 v[112:115], v238 offset:36864
	v_add_f32_e64 v98, v138, v98
	v_add_f32_e64 v99, v139, v99
	v_add_f32_e64 v96, v136, v96
	v_add_f32_e64 v97, v137, v97
	v_pk_add_f32 v[98:99], v[142:143], v[98:99]
	v_pk_add_f32 v[96:97], v[140:141], v[96:97]
	s_waitcnt lgkmcnt(0)
	v_mfma_f32_32x32x16_bf16 v[16:31], v[132:135], v[116:119], v[16:31]
	ds_read_b128 v[120:123], v238 offset:40960
	v_add_f32_e64 v98, v180, v98
	v_add_f32_e64 v99, v181, v99
	v_add_f32_e64 v96, v178, v96
	v_add_f32_e64 v97, v179, v97
	v_pk_add_f32 v[98:99], v[184:185], v[98:99]
	v_pk_add_f32 v[96:97], v[182:183], v[96:97]
	v_mfma_f32_32x32x16_bf16 v[0:15], v[100:103], v[116:119], v[0:15]
	ds_read_b128 v[124:127], v238 offset:45056
	v_mfma_f32_32x32x16_bf16 v[80:95], v[104:107], v[108:111], v[80:95]
	ds_read_b128 v[100:103], v239 offset:32768
	v_cvt_pk_bf16_f32 v116, v178, v179
	v_cvt_pk_bf16_f32 v117, v180, v181
	v_cvt_pk_bf16_f32 v118, v182, v183
	v_cvt_pk_bf16_f32 v119, v184, v185
	v_mfma_f32_32x32x16_bf16 v[64:79], v[112:115], v[108:111], v[64:79]
	ds_read_b128 v[104:107], v239 offset:36864
	s_waitcnt lgkmcnt(0)
	v_mfma_f32_32x32x16_bf16 v[16:31], v[120:123], v[108:111], v[16:31]
	ds_read_b128 v[112:115], v239 offset:40960
	v_mfma_f32_32x32x16_bf16 v[0:15], v[124:127], v[108:111], v[0:15]
	ds_read_b128 v[120:123], v239 offset:45056
	v_mfma_f32_32x32x16_bf16 v[80:95], v[100:103], v[116:119], v[80:95]
	v_mfma_f32_32x32x16_bf16 v[64:79], v[104:107], v[116:119], v[64:79]
	s_waitcnt lgkmcnt(0)
	v_mfma_f32_32x32x16_bf16 v[16:31], v[112:115], v[116:119], v[16:31]
	v_mfma_f32_32x32x16_bf16 v[0:15], v[120:123], v[116:119], v[0:15]
	s_waitcnt vmcnt(4) lgkmcnt(0)
	v_add_f32_e32 v100, v128, v129
	v_add_f32_e32 v101, v130, v131
	v_add_f32_e32 v100, v100, v101
	v_add_f32_e32 v96, v96, v97
	v_add_f32_e32 v97, v98, v99
	s_barrier
	v_add_f32_e32 v100, v177, v100
	v_add_f32_e32 v96, v96, v97
	v_add_f32_e32 v177, v100, v96
	s_add_u32 s98, s98, 0x30000
	s_addc_u32 s99, s99, 0
	s_add_u32 s100, s100, 0x100
	s_addc_u32 s101, s101, 0
	s_add_i32 s21, s21, 12
	s_addk_i32 s15, 0x300
	s_add_i32 s20, s20, 0x30000
	s_cmp_lt_u32 s21, 50
	s_cbranch_scc1 .Lst0_u6_loop
	s_cmp_lt_u32 s21, 60
	s_cbranch_scc1 .Lst0_single
.Lst0_exit:
	s_cmp_lg_u32 s21, 60
	s_cbranch_scc1 .Lst0_orig
	s_cmp_lg_u32 s41, 0
	s_cbranch_scc1 .Lst0_orig
	s_and_b32 s2, s20, 0xffff
	s_cmp_lg_u32 s2, 0xc000
	s_cbranch_scc1 .Lst0_orig
	s_mov_b32 s2, s40
	s_add_i32 s2, s2, s15
	s_sub_i32 s2, s2, 64
	s_mul_hi_i32 s3, s2, 0x600
	s_mulk_i32 s2, 0x600
	s_add_u32 s2, s12, s2
	s_addc_u32 s3, s13, s3
	s_add_i32 s46, s58, 0
	s_mov_b32 m0, s46
	s_nop 0
	global_load_lds_dwordx4 v198, s[2:3]
	s_add_i32 m0, s46, 0x400
	s_nop 0
	global_load_lds_dwordx4 v194, s[2:3]
	s_mov_b32 s46, s40
	s_add_i32 s46, s46, s15
	s_addk_i32 s46, 0xff80
	s_ashr_i32 s47, s46, 31
	s_lshl_b64 s[46:47], s[46:47], 1
	s_add_u32 s46, s39, s46
	s_addc_u32 s47, s67, s47
	s_add_i32 s48, s20, 0xffffc000
	s_add_i32 s48, s58, 0x8000
	s_add_i32 m0, s48, 0xc000
	s_nop 0
	global_load_lds_dwordx4 v196, s[46:47]
	s_add_i32 m0, s48, 0xc400
	s_nop 0
	global_load_lds_dwordx4 v192, s[46:47]
	s_add_i32 s46, s20, 0xffff4000
	ds_read_b128 v[96:99], v205 offset:16384
	ds_read_b128 v[100:103], v205 offset:24576
	v_exp_f32_e32 v140, v48
	v_exp_f32_e32 v141, v49
	v_exp_f32_e32 v142, v50
	v_exp_f32_e32 v143, v51
	s_waitcnt lgkmcnt(0)
	v_mfma_f32_32x32x16_bf16 v[112:127], v[96:99], v[160:163], 0
	ds_read_b128 v[128:131], v211 offset:16384
	ds_read_b128 v[132:135], v211 offset:24576
	ds_read_b128 v[136:139], v212 offset:16384
	ds_read_b128 v[48:51], v212 offset:24576
	v_mfma_f32_32x32x16_bf16 v[96:111], v[100:103], v[160:163], 0
	v_exp_f32_e32 v144, v52
	v_exp_f32_e32 v145, v53
	v_exp_f32_e32 v146, v54
	v_exp_f32_e32 v147, v55
	s_waitcnt lgkmcnt(0)
	v_mfma_f32_32x32x16_bf16 v[112:127], v[128:131], v[164:167], v[112:127]
	ds_read_b128 v[52:55], v213 offset:16384
	v_exp_f32_e32 v148, v56
	v_exp_f32_e32 v149, v57
	v_exp_f32_e32 v150, v58
	v_exp_f32_e32 v151, v59
	v_mfma_f32_32x32x16_bf16 v[96:111], v[132:135], v[164:167], v[96:111]
	ds_read_b128 v[56:59], v213 offset:24576
	v_exp_f32_e32 v128, v60
	v_exp_f32_e32 v129, v61
	v_exp_f32_e32 v130, v62
	v_exp_f32_e32 v131, v63
	v_mfma_f32_32x32x16_bf16 v[112:127], v[136:139], v[168:171], v[112:127]
	ds_read_b128 v[60:63], v206 offset:49152
	v_exp_f32_e32 v132, v32
	v_exp_f32_e32 v133, v33
	v_exp_f32_e32 v134, v34
	v_exp_f32_e32 v135, v35
	v_mfma_f32_32x32x16_bf16 v[96:111], v[48:51], v[168:171], v[96:111]
	ds_read_b128 v[32:35], v206 offset:53248
	v_exp_f32_e32 v136, v36
	v_exp_f32_e32 v137, v37
	v_exp_f32_e32 v138, v38
	v_exp_f32_e32 v139, v39
	s_waitcnt lgkmcnt(0)
	v_mfma_f32_32x32x16_bf16 v[112:127], v[52:55], v[172:175], v[112:127]
	ds_read_b128 v[36:39], v206 offset:57344
	v_exp_f32_e32 v152, v40
	v_exp_f32_e32 v153, v41
	v_exp_f32_e32 v154, v42
	v_exp_f32_e32 v155, v43
	v_mfma_f32_32x32x16_bf16 v[96:111], v[56:59], v[172:175], v[96:111]
	ds_read_b128 v[40:43], v206 offset:61440
	v_exp_f32_e32 v156, v44
	v_exp_f32_e32 v157, v45
	v_exp_f32_e32 v158, v46
	v_exp_f32_e32 v159, v47
	v_cvt_pk_bf16_f32 v44, v140, v141
	v_cvt_pk_bf16_f32 v45, v142, v143
	v_cvt_pk_bf16_f32 v46, v144, v145
	v_cvt_pk_bf16_f32 v47, v146, v147
	s_nop 1
	v_mfma_f32_32x32x16_bf16 v[80:95], v[60:63], v[44:47], v[80:95]
	ds_read_b128 v[48:51], v207 offset:49152
	v_cvt_pk_bf16_f32 v52, v148, v149
	v_cvt_pk_bf16_f32 v53, v150, v151
	v_cvt_pk_bf16_f32 v54, v128, v129
	v_cvt_pk_bf16_f32 v55, v130, v131
	v_mfma_f32_32x32x16_bf16 v[64:79], v[32:35], v[44:47], v[64:79]
	ds_read_b128 v[56:59], v207 offset:53248
	v_pk_add_f32 v[62:63], v[146:147], v[142:143]
	v_pk_add_f32 v[60:61], v[144:145], v[140:141]
	s_waitcnt lgkmcnt(0)
	v_mfma_f32_32x32x16_bf16 v[16:31], v[36:39], v[44:47], v[16:31]
	ds_read_b128 v[32:35], v207 offset:57344
	v_add_f32_e64 v62, v150, v62
	v_add_f32_e64 v63, v151, v63
	v_add_f32_e64 v60, v148, v60
	v_add_f32_e64 v61, v149, v61
	v_pk_add_f32 v[62:63], v[130:131], v[62:63]
	v_pk_add_f32 v[60:61], v[128:129], v[60:61]
	v_mfma_f32_32x32x16_bf16 v[0:15], v[40:43], v[44:47], v[0:15]
	ds_read_b128 v[36:39], v207 offset:61440
	v_mfma_f32_32x32x16_bf16 v[80:95], v[48:51], v[52:55], v[80:95]
	ds_read_b128 v[40:43], v208 offset:49152
	v_cvt_pk_bf16_f32 v44, v132, v133
	v_cvt_pk_bf16_f32 v45, v134, v135
	v_cvt_pk_bf16_f32 v46, v136, v137
	v_cvt_pk_bf16_f32 v47, v138, v139
	v_mfma_f32_32x32x16_bf16 v[64:79], v[56:59], v[52:55], v[64:79]
	ds_read_b128 v[48:51], v208 offset:53248
	v_add_f32_e64 v62, v134, v62
	v_add_f32_e64 v63, v135, v63
	v_add_f32_e64 v60, v132, v60
	v_add_f32_e64 v61, v133, v61
	v_pk_add_f32 v[62:63], v[138:139], v[62:63]
	v_pk_add_f32 v[60:61], v[136:137], v[60:61]
	s_waitcnt lgkmcnt(0)
	v_mfma_f32_32x32x16_bf16 v[16:31], v[32:35], v[52:55], v[16:31]
	ds_read_b128 v[56:59], v208 offset:57344
	v_add_f32_e64 v62, v154, v62
	v_add_f32_e64 v63, v155, v63
	v_add_f32_e64 v60, v152, v60
	v_add_f32_e64 v61, v153, v61
	v_pk_add_f32 v[130:131], v[158:159], v[62:63]
	v_pk_add_f32 v[128:129], v[156:157], v[60:61]
	v_mfma_f32_32x32x16_bf16 v[0:15], v[36:39], v[52:55], v[0:15]
	ds_read_b128 v[32:35], v208 offset:61440
	v_mfma_f32_32x32x16_bf16 v[80:95], v[40:43], v[44:47], v[80:95]
	ds_read_b128 v[36:39], v209 offset:49152
	v_cvt_pk_bf16_f32 v52, v152, v153
	v_cvt_pk_bf16_f32 v53, v154, v155
	v_cvt_pk_bf16_f32 v54, v156, v157
	v_cvt_pk_bf16_f32 v55, v158, v159
	v_mfma_f32_32x32x16_bf16 v[64:79], v[48:51], v[44:47], v[64:79]
	ds_read_b128 v[40:43], v209 offset:53248
	s_waitcnt lgkmcnt(0)
	v_mfma_f32_32x32x16_bf16 v[16:31], v[56:59], v[44:47], v[16:31]
	ds_read_b128 v[48:51], v209 offset:57344
	v_mfma_f32_32x32x16_bf16 v[0:15], v[32:35], v[44:47], v[0:15]
	ds_read_b128 v[56:59], v209 offset:61440
	v_mfma_f32_32x32x16_bf16 v[80:95], v[36:39], v[52:55], v[80:95]
	v_mfma_f32_32x32x16_bf16 v[64:79], v[40:43], v[52:55], v[64:79]
	s_waitcnt lgkmcnt(0)
	v_mfma_f32_32x32x16_bf16 v[16:31], v[48:51], v[52:55], v[16:31]
	v_mfma_f32_32x32x16_bf16 v[0:15], v[56:59], v[52:55], v[0:15]
	s_waitcnt vmcnt(4) lgkmcnt(0)
	s_barrier
	s_mov_b32 s68, s14
	s_add_i32 s68, s68, s15
	s_mul_hi_i32 s69, s68, 0x600
	s_mulk_i32 s68, 0x600
	s_add_u32 s68, s12, s68
	s_addc_u32 s69, s13, s69
	s_add_i32 s49, 0x4000, s57
	s_mov_b32 m0, s49
	s_nop 0
	global_load_lds_dwordx4 v198, s[68:69]
	s_add_i32 m0, s49, 0x400
	s_nop 0
	global_load_lds_dwordx4 v194, s[68:69]
	s_mov_b32 s44, s40
	s_add_i32 s44, s44, s15
	s_sub_i32 s44, s44, 64
	s_ashr_i32 s45, s44, 31
	s_lshl_b64 s[44:45], s[44:45], 1
	s_add_u32 s44, s39, s44
	s_addc_u32 s45, s67, s45
	s_add_i32 s49, s58, 0xc000
	s_add_i32 m0, s49, 0xc000
	s_nop 0
	global_load_lds_dwordx4 v196, s[44:45]
	s_add_i32 m0, s49, 0xc400
	s_nop 0
	global_load_lds_dwordx4 v192, s[44:45]
	v_exp_f32_e32 v144, v112
	ds_read_b128 v[32:35], v205 offset:32768
	ds_read_b128 v[36:39], v205 offset:40960
	v_exp_f32_e32 v145, v113
	v_exp_f32_e32 v146, v114
	v_exp_f32_e32 v147, v115
	s_waitcnt lgkmcnt(0)
	v_mfma_f32_32x32x16_bf16 v[48:63], v[32:35], v[160:163], 0
	ds_read_b128 v[132:135], v211 offset:32768
	ds_read_b128 v[136:139], v211 offset:40960
	ds_read_b128 v[140:143], v212 offset:32768
	ds_read_b128 v[112:115], v212 offset:40960
	v_mfma_f32_32x32x16_bf16 v[32:47], v[36:39], v[160:163], 0
	v_exp_f32_e32 v148, v116
	v_exp_f32_e32 v149, v117
	v_exp_f32_e32 v150, v118
	v_exp_f32_e32 v151, v119
	s_waitcnt lgkmcnt(0)
	v_mfma_f32_32x32x16_bf16 v[48:63], v[132:135], v[164:167], v[48:63]
	ds_read_b128 v[116:119], v213 offset:32768
	v_exp_f32_e32 v152, v120
	v_exp_f32_e32 v153, v121
	v_exp_f32_e32 v154, v122
	v_exp_f32_e32 v155, v123
	v_mfma_f32_32x32x16_bf16 v[32:47], v[136:139], v[164:167], v[32:47]
	ds_read_b128 v[120:123], v213 offset:40960
	v_exp_f32_e32 v156, v124
	v_exp_f32_e32 v157, v125
	v_exp_f32_e32 v158, v126
	v_exp_f32_e32 v159, v127
	v_mfma_f32_32x32x16_bf16 v[48:63], v[140:143], v[168:171], v[48:63]
	ds_read_b128 v[124:127], v236
	v_exp_f32_e32 v136, v96
	v_exp_f32_e32 v137, v97
	v_exp_f32_e32 v138, v98
	v_exp_f32_e32 v139, v99
	v_mfma_f32_32x32x16_bf16 v[32:47], v[112:115], v[168:171], v[32:47]
	ds_read_b128 v[96:99], v236 offset:4096
	v_exp_f32_e32 v140, v100
	v_exp_f32_e32 v141, v101
	v_exp_f32_e32 v142, v102
	v_exp_f32_e32 v143, v103
	s_waitcnt lgkmcnt(0)
	v_mfma_f32_32x32x16_bf16 v[48:63], v[116:119], v[172:175], v[48:63]
	ds_read_b128 v[100:103], v236 offset:8192
	v_exp_f32_e32 v178, v104
	v_exp_f32_e32 v179, v105
	v_exp_f32_e32 v180, v106
	v_exp_f32_e32 v181, v107
	v_mfma_f32_32x32x16_bf16 v[32:47], v[120:123], v[172:175], v[32:47]
	ds_read_b128 v[104:107], v236 offset:12288
	v_exp_f32_e32 v182, v108
	v_exp_f32_e32 v183, v109
	v_exp_f32_e32 v184, v110
	v_exp_f32_e32 v185, v111
	v_cvt_pk_bf16_f32 v108, v144, v145
	v_cvt_pk_bf16_f32 v109, v146, v147
	v_cvt_pk_bf16_f32 v110, v148, v149
	v_cvt_pk_bf16_f32 v111, v150, v151
	s_nop 1
	v_mfma_f32_32x32x16_bf16 v[80:95], v[124:127], v[108:111], v[80:95]
	ds_read_b128 v[112:115], v237
	v_cvt_pk_bf16_f32 v116, v152, v153
	v_cvt_pk_bf16_f32 v117, v154, v155
	v_cvt_pk_bf16_f32 v118, v156, v157
	v_cvt_pk_bf16_f32 v119, v158, v159
	v_mfma_f32_32x32x16_bf16 v[64:79], v[96:99], v[108:111], v[64:79]
	ds_read_b128 v[120:123], v237 offset:4096
	v_pk_add_f32 v[126:127], v[150:151], v[146:147]
	v_pk_add_f32 v[124:125], v[148:149], v[144:145]
	s_waitcnt lgkmcnt(0)
	v_mfma_f32_32x32x16_bf16 v[16:31], v[100:103], v[108:111], v[16:31]
	ds_read_b128 v[132:135], v237 offset:8192
	v_add_f32_e64 v98, v154, v126
	v_add_f32_e64 v99, v155, v127
	v_add_f32_e64 v96, v152, v124
	v_add_f32_e64 v97, v153, v125
	v_pk_add_f32 v[98:99], v[158:159], v[98:99]
	v_pk_add_f32 v[96:97], v[156:157], v[96:97]
	v_mfma_f32_32x32x16_bf16 v[0:15], v[104:107], v[108:111], v[0:15]
	ds_read_b128 v[100:103], v237 offset:12288
	v_mfma_f32_32x32x16_bf16 v[80:95], v[112:115], v[116:119], v[80:95]
	ds_read_b128 v[104:107], v238
	v_cvt_pk_bf16_f32 v108, v136, v137
	v_cvt_pk_bf16_f32 v109, v138, v139
	v_cvt_pk_bf16_f32 v110, v140, v141
	v_cvt_pk_bf16_f32 v111, v142, v143
	v_mfma_f32_32x32x16_bf16 v[64:79], v[120:123], v[116:119], v[64:79]
	ds_read_b128 v[112:115], v238 offset:4096
	v_add_f32_e64 v98, v138, v98
	v_add_f32_e64 v99, v139, v99
	v_add_f32_e64 v96, v136, v96
	v_add_f32_e64 v97, v137, v97
	v_pk_add_f32 v[98:99], v[142:143], v[98:99]
	v_pk_add_f32 v[96:97], v[140:141], v[96:97]
	s_waitcnt lgkmcnt(0)
	v_mfma_f32_32x32x16_bf16 v[16:31], v[132:135], v[116:119], v[16:31]
	ds_read_b128 v[120:123], v238 offset:8192
	v_add_f32_e64 v98, v180, v98
	v_add_f32_e64 v99, v181, v99
	v_add_f32_e64 v96, v178, v96
	v_add_f32_e64 v97, v179, v97
	v_pk_add_f32 v[98:99], v[184:185], v[98:99]
	v_pk_add_f32 v[96:97], v[182:183], v[96:97]
	v_mfma_f32_32x32x16_bf16 v[0:15], v[100:103], v[116:119], v[0:15]
	ds_read_b128 v[124:127], v238 offset:12288
	v_mfma_f32_32x32x16_bf16 v[80:95], v[104:107], v[108:111], v[80:95]
	ds_read_b128 v[100:103], v239
	v_cvt_pk_bf16_f32 v116, v178, v179
	v_cvt_pk_bf16_f32 v117, v180, v181
	v_cvt_pk_bf16_f32 v118, v182, v183
	v_cvt_pk_bf16_f32 v119, v184, v185
	v_mfma_f32_32x32x16_bf16 v[64:79], v[112:115], v[108:111], v[64:79]
	ds_read_b128 v[104:107], v239 offset:4096
	s_waitcnt lgkmcnt(0)
	v_mfma_f32_32x32x16_bf16 v[16:31], v[120:123], v[108:111], v[16:31]
	ds_read_b128 v[112:115], v239 offset:8192
	v_mfma_f32_32x32x16_bf16 v[0:15], v[124:127], v[108:111], v[0:15]
	ds_read_b128 v[120:123], v239 offset:12288
	v_mfma_f32_32x32x16_bf16 v[80:95], v[100:103], v[116:119], v[80:95]
	v_mfma_f32_32x32x16_bf16 v[64:79], v[104:107], v[116:119], v[64:79]
	s_waitcnt lgkmcnt(0)
	v_mfma_f32_32x32x16_bf16 v[16:31], v[112:115], v[116:119], v[16:31]
	v_mfma_f32_32x32x16_bf16 v[0:15], v[120:123], v[116:119], v[0:15]
	s_waitcnt vmcnt(4) lgkmcnt(0)
	v_add_f32_e32 v100, v128, v129
	v_add_f32_e32 v101, v130, v131
	v_add_f32_e32 v100, v100, v101
	v_add_f32_e32 v96, v96, v97
	v_add_f32_e32 v97, v98, v99
	s_barrier
	v_add_f32_e32 v100, v177, v100
	v_add_f32_e32 v96, v96, v97
	v_add_f32_e32 v177, v100, v96
	s_add_i32 s21, s21, 2
	s_addk_i32 s15, 0x80
	s_add_i32 s20, s20, 0x8000
	s_mov_b32 s2, s14
	s_add_i32 s2, s2, s15
	s_sub_i32 s2, s2, 64
	s_mul_hi_i32 s3, s2, 0x600
	s_mulk_i32 s2, 0x600
	s_add_u32 s2, s12, s2
	s_addc_u32 s3, s13, s3
	s_add_i32 s46, s58, 0x8000
	s_mov_b32 m0, s46
	s_nop 0
	global_load_lds_dwordx4 v198, s[2:3]
	s_add_i32 m0, s46, 0x400
	s_nop 0
	global_load_lds_dwordx4 v194, s[2:3]
	s_mov_b32 s46, s14
	s_add_i32 s46, s46, s15
	s_addk_i32 s46, 0xff80
	s_ashr_i32 s47, s46, 31
	s_lshl_b64 s[46:47], s[46:47], 1
	s_add_u32 s46, s39, s46
	s_addc_u32 s47, s67, s47
	s_add_i32 s48, s20, 0xffffc000
	s_add_i32 s48, s58, 0
	s_add_i32 m0, s48, 0xc000
	s_nop 0
	global_load_lds_dwordx4 v196, s[46:47]
	s_add_i32 m0, s48, 0xc400
	s_nop 0
	global_load_lds_dwordx4 v192, s[46:47]
	s_add_i32 s46, s20, 0xffff4000
	ds_read_b128 v[96:99], v205
	ds_read_b128 v[100:103], v205 offset:8192
	v_exp_f32_e32 v140, v48
	v_exp_f32_e32 v141, v49
	v_exp_f32_e32 v142, v50
	v_exp_f32_e32 v143, v51
	s_waitcnt lgkmcnt(0)
	v_mfma_f32_32x32x16_bf16 v[112:127], v[96:99], v[160:163], 0
	ds_read_b128 v[128:131], v211
	ds_read_b128 v[132:135], v211 offset:8192
	ds_read_b128 v[136:139], v212
	ds_read_b128 v[48:51], v212 offset:8192
	v_mfma_f32_32x32x16_bf16 v[96:111], v[100:103], v[160:163], 0
	v_exp_f32_e32 v144, v52
	v_exp_f32_e32 v145, v53
	v_exp_f32_e32 v146, v54
	v_exp_f32_e32 v147, v55
	s_waitcnt lgkmcnt(0)
	v_mfma_f32_32x32x16_bf16 v[112:127], v[128:131], v[164:167], v[112:127]
	ds_read_b128 v[52:55], v213
	v_exp_f32_e32 v148, v56
	v_exp_f32_e32 v149, v57
	v_exp_f32_e32 v150, v58
	v_exp_f32_e32 v151, v59
	v_mfma_f32_32x32x16_bf16 v[96:111], v[132:135], v[164:167], v[96:111]
	ds_read_b128 v[56:59], v213 offset:8192
	v_exp_f32_e32 v128, v60
	v_exp_f32_e32 v129, v61
	v_exp_f32_e32 v130, v62
	v_exp_f32_e32 v131, v63
	v_mfma_f32_32x32x16_bf16 v[112:127], v[136:139], v[168:171], v[112:127]
	ds_read_b128 v[60:63], v236 offset:16384
	v_exp_f32_e32 v132, v32
	v_exp_f32_e32 v133, v33
	v_exp_f32_e32 v134, v34
	v_exp_f32_e32 v135, v35
	v_mfma_f32_32x32x16_bf16 v[96:111], v[48:51], v[168:171], v[96:111]
	ds_read_b128 v[32:35], v236 offset:20480
	v_exp_f32_e32 v136, v36
	v_exp_f32_e32 v137, v37
	v_exp_f32_e32 v138, v38
	v_exp_f32_e32 v139, v39
	s_waitcnt lgkmcnt(0)
	v_mfma_f32_32x32x16_bf16 v[112:127], v[52:55], v[172:175], v[112:127]
	ds_read_b128 v[36:39], v236 offset:24576
	v_exp_f32_e32 v152, v40
	v_exp_f32_e32 v153, v41
	v_exp_f32_e32 v154, v42
	v_exp_f32_e32 v155, v43
	v_mfma_f32_32x32x16_bf16 v[96:111], v[56:59], v[172:175], v[96:111]
	ds_read_b128 v[40:43], v236 offset:28672
	v_exp_f32_e32 v156, v44
	v_exp_f32_e32 v157, v45
	v_exp_f32_e32 v158, v46
	v_exp_f32_e32 v159, v47
	v_cvt_pk_bf16_f32 v44, v140, v141
	v_cvt_pk_bf16_f32 v45, v142, v143
	v_cvt_pk_bf16_f32 v46, v144, v145
	v_cvt_pk_bf16_f32 v47, v146, v147
	s_nop 1
	v_mfma_f32_32x32x16_bf16 v[80:95], v[60:63], v[44:47], v[80:95]
	ds_read_b128 v[48:51], v237 offset:16384
	v_cvt_pk_bf16_f32 v52, v148, v149
	v_cvt_pk_bf16_f32 v53, v150, v151
	v_cvt_pk_bf16_f32 v54, v128, v129
	v_cvt_pk_bf16_f32 v55, v130, v131
	v_mfma_f32_32x32x16_bf16 v[64:79], v[32:35], v[44:47], v[64:79]
	ds_read_b128 v[56:59], v237 offset:20480
	v_pk_add_f32 v[62:63], v[146:147], v[142:143]
	v_pk_add_f32 v[60:61], v[144:145], v[140:141]
	s_waitcnt lgkmcnt(0)
	v_mfma_f32_32x32x16_bf16 v[16:31], v[36:39], v[44:47], v[16:31]
	ds_read_b128 v[32:35], v237 offset:24576
	v_add_f32_e64 v62, v150, v62
	v_add_f32_e64 v63, v151, v63
	v_add_f32_e64 v60, v148, v60
	v_add_f32_e64 v61, v149, v61
	v_pk_add_f32 v[62:63], v[130:131], v[62:63]
	v_pk_add_f32 v[60:61], v[128:129], v[60:61]
	v_mfma_f32_32x32x16_bf16 v[0:15], v[40:43], v[44:47], v[0:15]
	ds_read_b128 v[36:39], v237 offset:28672
	v_mfma_f32_32x32x16_bf16 v[80:95], v[48:51], v[52:55], v[80:95]
	ds_read_b128 v[40:43], v238 offset:16384
	v_cvt_pk_bf16_f32 v44, v132, v133
	v_cvt_pk_bf16_f32 v45, v134, v135
	v_cvt_pk_bf16_f32 v46, v136, v137
	v_cvt_pk_bf16_f32 v47, v138, v139
	v_mfma_f32_32x32x16_bf16 v[64:79], v[56:59], v[52:55], v[64:79]
	ds_read_b128 v[48:51], v238 offset:20480
	v_add_f32_e64 v62, v134, v62
	v_add_f32_e64 v63, v135, v63
	v_add_f32_e64 v60, v132, v60
	v_add_f32_e64 v61, v133, v61
	v_pk_add_f32 v[62:63], v[138:139], v[62:63]
	v_pk_add_f32 v[60:61], v[136:137], v[60:61]
	s_waitcnt lgkmcnt(0)
	v_mfma_f32_32x32x16_bf16 v[16:31], v[32:35], v[52:55], v[16:31]
	ds_read_b128 v[56:59], v238 offset:24576
	v_add_f32_e64 v62, v154, v62
	v_add_f32_e64 v63, v155, v63
	v_add_f32_e64 v60, v152, v60
	v_add_f32_e64 v61, v153, v61
	v_pk_add_f32 v[130:131], v[158:159], v[62:63]
	v_pk_add_f32 v[128:129], v[156:157], v[60:61]
	v_mfma_f32_32x32x16_bf16 v[0:15], v[36:39], v[52:55], v[0:15]
	ds_read_b128 v[32:35], v238 offset:28672
	v_mfma_f32_32x32x16_bf16 v[80:95], v[40:43], v[44:47], v[80:95]
	ds_read_b128 v[36:39], v239 offset:16384
	v_cvt_pk_bf16_f32 v52, v152, v153
	v_cvt_pk_bf16_f32 v53, v154, v155
	v_cvt_pk_bf16_f32 v54, v156, v157
	v_cvt_pk_bf16_f32 v55, v158, v159
	v_mfma_f32_32x32x16_bf16 v[64:79], v[48:51], v[44:47], v[64:79]
	ds_read_b128 v[40:43], v239 offset:20480
	s_waitcnt lgkmcnt(0)
	v_mfma_f32_32x32x16_bf16 v[16:31], v[56:59], v[44:47], v[16:31]
	ds_read_b128 v[48:51], v239 offset:24576
	v_mfma_f32_32x32x16_bf16 v[0:15], v[32:35], v[44:47], v[0:15]
	ds_read_b128 v[56:59], v239 offset:28672
	v_mfma_f32_32x32x16_bf16 v[80:95], v[36:39], v[52:55], v[80:95]
	v_mfma_f32_32x32x16_bf16 v[64:79], v[40:43], v[52:55], v[64:79]
	s_waitcnt lgkmcnt(0)
	v_mfma_f32_32x32x16_bf16 v[16:31], v[48:51], v[52:55], v[16:31]
	v_mfma_f32_32x32x16_bf16 v[0:15], v[56:59], v[52:55], v[0:15]
	s_waitcnt vmcnt(4) lgkmcnt(0)
	s_barrier
	s_mov_b32 s68, s14
	s_add_i32 s68, s68, s15
	s_mul_hi_i32 s69, s68, 0x600
	s_mulk_i32 s68, 0x600
	s_add_u32 s68, s12, s68
	s_addc_u32 s69, s13, s69
	s_add_i32 s49, 0, s57
	s_mov_b32 m0, s49
	s_nop 0
	global_load_lds_dwordx4 v198, s[68:69]
	s_add_i32 m0, s49, 0x400
	s_nop 0
	global_load_lds_dwordx4 v194, s[68:69]
	s_mov_b32 s44, s14
	s_add_i32 s44, s44, s15
	s_sub_i32 s44, s44, 64
	s_ashr_i32 s45, s44, 31
	s_lshl_b64 s[44:45], s[44:45], 1
	s_add_u32 s44, s39, s44
	s_addc_u32 s45, s67, s45
	s_add_i32 s49, s58, 0x4000
	s_add_i32 m0, s49, 0xc000
	s_nop 0
	global_load_lds_dwordx4 v196, s[44:45]
	s_add_i32 m0, s49, 0xc400
	s_nop 0
	global_load_lds_dwordx4 v192, s[44:45]
	v_exp_f32_e32 v144, v112
	ds_read_b128 v[32:35], v205 offset:16384
	ds_read_b128 v[36:39], v205 offset:24576
	v_exp_f32_e32 v145, v113
	v_exp_f32_e32 v146, v114
	v_exp_f32_e32 v147, v115
	s_waitcnt lgkmcnt(0)
	v_mfma_f32_32x32x16_bf16 v[48:63], v[32:35], v[160:163], 0
	ds_read_b128 v[132:135], v211 offset:16384
	ds_read_b128 v[136:139], v211 offset:24576
	ds_read_b128 v[140:143], v212 offset:16384
	ds_read_b128 v[112:115], v212 offset:24576
	v_mfma_f32_32x32x16_bf16 v[32:47], v[36:39], v[160:163], 0
	v_exp_f32_e32 v148, v116
	v_exp_f32_e32 v149, v117
	v_exp_f32_e32 v150, v118
	v_exp_f32_e32 v151, v119
	s_waitcnt lgkmcnt(0)
	v_mfma_f32_32x32x16_bf16 v[48:63], v[132:135], v[164:167], v[48:63]
	ds_read_b128 v[116:119], v213 offset:16384
	v_exp_f32_e32 v152, v120
	v_exp_f32_e32 v153, v121
	v_exp_f32_e32 v154, v122
	v_exp_f32_e32 v155, v123
	v_mfma_f32_32x32x16_bf16 v[32:47], v[136:139], v[164:167], v[32:47]
	ds_read_b128 v[120:123], v213 offset:24576
	v_exp_f32_e32 v156, v124
	v_exp_f32_e32 v157, v125
	v_exp_f32_e32 v158, v126
	v_exp_f32_e32 v159, v127
	v_mfma_f32_32x32x16_bf16 v[48:63], v[140:143], v[168:171], v[48:63]
	ds_read_b128 v[124:127], v236 offset:32768
	v_exp_f32_e32 v136, v96
	v_exp_f32_e32 v137, v97
	v_exp_f32_e32 v138, v98
	v_exp_f32_e32 v139, v99
	v_mfma_f32_32x32x16_bf16 v[32:47], v[112:115], v[168:171], v[32:47]
	ds_read_b128 v[96:99], v236 offset:36864
	v_exp_f32_e32 v140, v100
	v_exp_f32_e32 v141, v101
	v_exp_f32_e32 v142, v102
	v_exp_f32_e32 v143, v103
	s_waitcnt lgkmcnt(0)
	v_mfma_f32_32x32x16_bf16 v[48:63], v[116:119], v[172:175], v[48:63]
	ds_read_b128 v[100:103], v236 offset:40960
	v_exp_f32_e32 v178, v104
	v_exp_f32_e32 v179, v105
	v_exp_f32_e32 v180, v106
	v_exp_f32_e32 v181, v107
	v_mfma_f32_32x32x16_bf16 v[32:47], v[120:123], v[172:175], v[32:47]
	ds_read_b128 v[104:107], v236 offset:45056
	v_exp_f32_e32 v182, v108
	v_exp_f32_e32 v183, v109
	v_exp_f32_e32 v184, v110
	v_exp_f32_e32 v185, v111
	v_cvt_pk_bf16_f32 v108, v144, v145
	v_cvt_pk_bf16_f32 v109, v146, v147
	v_cvt_pk_bf16_f32 v110, v148, v149
	v_cvt_pk_bf16_f32 v111, v150, v151
	s_nop 1
	v_mfma_f32_32x32x16_bf16 v[80:95], v[124:127], v[108:111], v[80:95]
	ds_read_b128 v[112:115], v237 offset:32768
	v_cvt_pk_bf16_f32 v116, v152, v153
	v_cvt_pk_bf16_f32 v117, v154, v155
	v_cvt_pk_bf16_f32 v118, v156, v157
	v_cvt_pk_bf16_f32 v119, v158, v159
	v_mfma_f32_32x32x16_bf16 v[64:79], v[96:99], v[108:111], v[64:79]
	ds_read_b128 v[120:123], v237 offset:36864
	v_pk_add_f32 v[126:127], v[150:151], v[146:147]
	v_pk_add_f32 v[124:125], v[148:149], v[144:145]
	s_waitcnt lgkmcnt(0)
	v_mfma_f32_32x32x16_bf16 v[16:31], v[100:103], v[108:111], v[16:31]
	ds_read_b128 v[132:135], v237 offset:40960
	v_add_f32_e64 v98, v154, v126
	v_add_f32_e64 v99, v155, v127
	v_add_f32_e64 v96, v152, v124
	v_add_f32_e64 v97, v153, v125
	v_pk_add_f32 v[98:99], v[158:159], v[98:99]
	v_pk_add_f32 v[96:97], v[156:157], v[96:97]
	v_mfma_f32_32x32x16_bf16 v[0:15], v[104:107], v[108:111], v[0:15]
	ds_read_b128 v[100:103], v237 offset:45056
	v_mfma_f32_32x32x16_bf16 v[80:95], v[112:115], v[116:119], v[80:95]
	ds_read_b128 v[104:107], v238 offset:32768
	v_cvt_pk_bf16_f32 v108, v136, v137
	v_cvt_pk_bf16_f32 v109, v138, v139
	v_cvt_pk_bf16_f32 v110, v140, v141
	v_cvt_pk_bf16_f32 v111, v142, v143
	v_mfma_f32_32x32x16_bf16 v[64:79], v[120:123], v[116:119], v[64:79]
	ds_read_b128 v[112:115], v238 offset:36864
	v_add_f32_e64 v98, v138, v98
	v_add_f32_e64 v99, v139, v99
	v_add_f32_e64 v96, v136, v96
	v_add_f32_e64 v97, v137, v97
	v_pk_add_f32 v[98:99], v[142:143], v[98:99]
	v_pk_add_f32 v[96:97], v[140:141], v[96:97]
	s_waitcnt lgkmcnt(0)
	v_mfma_f32_32x32x16_bf16 v[16:31], v[132:135], v[116:119], v[16:31]
	ds_read_b128 v[120:123], v238 offset:40960
	v_add_f32_e64 v98, v180, v98
	v_add_f32_e64 v99, v181, v99
	v_add_f32_e64 v96, v178, v96
	v_add_f32_e64 v97, v179, v97
	v_pk_add_f32 v[98:99], v[184:185], v[98:99]
	v_pk_add_f32 v[96:97], v[182:183], v[96:97]
	v_mfma_f32_32x32x16_bf16 v[0:15], v[100:103], v[116:119], v[0:15]
	ds_read_b128 v[124:127], v238 offset:45056
	v_mfma_f32_32x32x16_bf16 v[80:95], v[104:107], v[108:111], v[80:95]
	ds_read_b128 v[100:103], v239 offset:32768
	v_cvt_pk_bf16_f32 v116, v178, v179
	v_cvt_pk_bf16_f32 v117, v180, v181
	v_cvt_pk_bf16_f32 v118, v182, v183
	v_cvt_pk_bf16_f32 v119, v184, v185
	v_mfma_f32_32x32x16_bf16 v[64:79], v[112:115], v[108:111], v[64:79]
	ds_read_b128 v[104:107], v239 offset:36864
	s_waitcnt lgkmcnt(0)
	v_mfma_f32_32x32x16_bf16 v[16:31], v[120:123], v[108:111], v[16:31]
	ds_read_b128 v[112:115], v239 offset:40960
	v_mfma_f32_32x32x16_bf16 v[0:15], v[124:127], v[108:111], v[0:15]
	ds_read_b128 v[120:123], v239 offset:45056
	v_mfma_f32_32x32x16_bf16 v[80:95], v[100:103], v[116:119], v[80:95]
	v_mfma_f32_32x32x16_bf16 v[64:79], v[104:107], v[116:119], v[64:79]
	s_waitcnt lgkmcnt(0)
	v_mfma_f32_32x32x16_bf16 v[16:31], v[112:115], v[116:119], v[16:31]
	v_mfma_f32_32x32x16_bf16 v[0:15], v[120:123], v[116:119], v[0:15]
	s_waitcnt vmcnt(4) lgkmcnt(0)
	v_add_f32_e32 v100, v128, v129
	v_add_f32_e32 v101, v130, v131
	v_add_f32_e32 v100, v100, v101
	v_add_f32_e32 v96, v96, v97
	v_add_f32_e32 v97, v98, v99
	s_barrier
	v_add_f32_e32 v100, v177, v100
	v_add_f32_e32 v96, v96, v97
	v_add_f32_e32 v177, v100, v96
	s_add_i32 s21, s21, 2
	s_addk_i32 s15, 0x80
	s_add_i32 s20, s20, 0x8000
	s_mov_b32 s2, s14
	s_add_i32 s2, s2, s15
	s_sub_i32 s2, s2, 64
	s_mul_hi_i32 s3, s2, 0x600
	s_mulk_i32 s2, 0x600
	s_add_u32 s2, s12, s2
	s_addc_u32 s3, s13, s3
	s_add_i32 s46, s58, 0x4000
	s_mov_b32 m0, s46
	s_nop 0
	global_load_lds_dwordx4 v198, s[2:3]
	s_add_i32 m0, s46, 0x400
	s_nop 0
	global_load_lds_dwordx4 v194, s[2:3]
	s_mov_b32 s46, s14
	s_add_i32 s46, s46, s15
	s_addk_i32 s46, 0xff80
	s_ashr_i32 s47, s46, 31
	s_lshl_b64 s[46:47], s[46:47], 1
	s_add_u32 s46, s39, s46
	s_addc_u32 s47, s67, s47
	s_add_i32 s48, s20, 0xffffc000
	s_add_i32 s48, s58, 0x8000
	s_add_i32 m0, s48, 0xc000
	s_nop 0
	global_load_lds_dwordx4 v196, s[46:47]
	s_add_i32 m0, s48, 0xc400
	s_nop 0
	global_load_lds_dwordx4 v192, s[46:47]
	s_add_i32 s46, s20, 0xffff4000
	ds_read_b128 v[96:99], v205 offset:32768
	ds_read_b128 v[100:103], v205 offset:40960
	v_exp_f32_e32 v140, v48
	v_exp_f32_e32 v141, v49
	v_exp_f32_e32 v142, v50
	v_exp_f32_e32 v143, v51
	s_waitcnt lgkmcnt(0)
	v_mfma_f32_32x32x16_bf16 v[112:127], v[96:99], v[160:163], 0
	ds_read_b128 v[128:131], v211 offset:32768
	ds_read_b128 v[132:135], v211 offset:40960
	ds_read_b128 v[136:139], v212 offset:32768
	ds_read_b128 v[48:51], v212 offset:40960
	v_mfma_f32_32x32x16_bf16 v[96:111], v[100:103], v[160:163], 0
	v_exp_f32_e32 v144, v52
	v_exp_f32_e32 v145, v53
	v_exp_f32_e32 v146, v54
	v_exp_f32_e32 v147, v55
	s_waitcnt lgkmcnt(0)
	v_mfma_f32_32x32x16_bf16 v[112:127], v[128:131], v[164:167], v[112:127]
	ds_read_b128 v[52:55], v213 offset:32768
	v_exp_f32_e32 v148, v56
	v_exp_f32_e32 v149, v57
	v_exp_f32_e32 v150, v58
	v_exp_f32_e32 v151, v59
	v_mfma_f32_32x32x16_bf16 v[96:111], v[132:135], v[164:167], v[96:111]
	ds_read_b128 v[56:59], v213 offset:40960
	v_exp_f32_e32 v128, v60
	v_exp_f32_e32 v129, v61
	v_exp_f32_e32 v130, v62
	v_exp_f32_e32 v131, v63
	v_mfma_f32_32x32x16_bf16 v[112:127], v[136:139], v[168:171], v[112:127]
	ds_read_b128 v[60:63], v206 offset:49152
	v_exp_f32_e32 v132, v32
	v_exp_f32_e32 v133, v33
	v_exp_f32_e32 v134, v34
	v_exp_f32_e32 v135, v35
	v_mfma_f32_32x32x16_bf16 v[96:111], v[48:51], v[168:171], v[96:111]
	ds_read_b128 v[32:35], v206 offset:53248
	v_exp_f32_e32 v136, v36
	v_exp_f32_e32 v137, v37
	v_exp_f32_e32 v138, v38
	v_exp_f32_e32 v139, v39
	s_waitcnt lgkmcnt(0)
	v_mfma_f32_32x32x16_bf16 v[112:127], v[52:55], v[172:175], v[112:127]
	ds_read_b128 v[36:39], v206 offset:57344
	v_exp_f32_e32 v152, v40
	v_exp_f32_e32 v153, v41
	v_exp_f32_e32 v154, v42
	v_exp_f32_e32 v155, v43
	v_mfma_f32_32x32x16_bf16 v[96:111], v[56:59], v[172:175], v[96:111]
	ds_read_b128 v[40:43], v206 offset:61440
	v_exp_f32_e32 v156, v44
	v_exp_f32_e32 v157, v45
	v_exp_f32_e32 v158, v46
	v_exp_f32_e32 v159, v47
	v_cvt_pk_bf16_f32 v44, v140, v141
	v_cvt_pk_bf16_f32 v45, v142, v143
	v_cvt_pk_bf16_f32 v46, v144, v145
	v_cvt_pk_bf16_f32 v47, v146, v147
	s_nop 1
	v_mfma_f32_32x32x16_bf16 v[80:95], v[60:63], v[44:47], v[80:95]
	ds_read_b128 v[48:51], v207 offset:49152
	v_cvt_pk_bf16_f32 v52, v148, v149
	v_cvt_pk_bf16_f32 v53, v150, v151
	v_cvt_pk_bf16_f32 v54, v128, v129
	v_cvt_pk_bf16_f32 v55, v130, v131
	v_mfma_f32_32x32x16_bf16 v[64:79], v[32:35], v[44:47], v[64:79]
	ds_read_b128 v[56:59], v207 offset:53248
	v_pk_add_f32 v[62:63], v[146:147], v[142:143]
	v_pk_add_f32 v[60:61], v[144:145], v[140:141]
	s_waitcnt lgkmcnt(0)
	v_mfma_f32_32x32x16_bf16 v[16:31], v[36:39], v[44:47], v[16:31]
	ds_read_b128 v[32:35], v207 offset:57344
	v_add_f32_e64 v62, v150, v62
	v_add_f32_e64 v63, v151, v63
	v_add_f32_e64 v60, v148, v60
	v_add_f32_e64 v61, v149, v61
	v_pk_add_f32 v[62:63], v[130:131], v[62:63]
	v_pk_add_f32 v[60:61], v[128:129], v[60:61]
	v_mfma_f32_32x32x16_bf16 v[0:15], v[40:43], v[44:47], v[0:15]
	ds_read_b128 v[36:39], v207 offset:61440
	v_mfma_f32_32x32x16_bf16 v[80:95], v[48:51], v[52:55], v[80:95]
	ds_read_b128 v[40:43], v208 offset:49152
	v_cvt_pk_bf16_f32 v44, v132, v133
	v_cvt_pk_bf16_f32 v45, v134, v135
	v_cvt_pk_bf16_f32 v46, v136, v137
	v_cvt_pk_bf16_f32 v47, v138, v139
	v_mfma_f32_32x32x16_bf16 v[64:79], v[56:59], v[52:55], v[64:79]
	ds_read_b128 v[48:51], v208 offset:53248
	v_add_f32_e64 v62, v134, v62
	v_add_f32_e64 v63, v135, v63
	v_add_f32_e64 v60, v132, v60
	v_add_f32_e64 v61, v133, v61
	v_pk_add_f32 v[62:63], v[138:139], v[62:63]
	v_pk_add_f32 v[60:61], v[136:137], v[60:61]
	s_waitcnt lgkmcnt(0)
	v_mfma_f32_32x32x16_bf16 v[16:31], v[32:35], v[52:55], v[16:31]
	ds_read_b128 v[56:59], v208 offset:57344
	v_add_f32_e64 v62, v154, v62
	v_add_f32_e64 v63, v155, v63
	v_add_f32_e64 v60, v152, v60
	v_add_f32_e64 v61, v153, v61
	v_pk_add_f32 v[130:131], v[158:159], v[62:63]
	v_pk_add_f32 v[128:129], v[156:157], v[60:61]
	v_mfma_f32_32x32x16_bf16 v[0:15], v[36:39], v[52:55], v[0:15]
	ds_read_b128 v[32:35], v208 offset:61440
	v_mfma_f32_32x32x16_bf16 v[80:95], v[40:43], v[44:47], v[80:95]
	ds_read_b128 v[36:39], v209 offset:49152
	v_cvt_pk_bf16_f32 v52, v152, v153
	v_cvt_pk_bf16_f32 v53, v154, v155
	v_cvt_pk_bf16_f32 v54, v156, v157
	v_cvt_pk_bf16_f32 v55, v158, v159
	v_mfma_f32_32x32x16_bf16 v[64:79], v[48:51], v[44:47], v[64:79]
	ds_read_b128 v[40:43], v209 offset:53248
	s_waitcnt lgkmcnt(0)
	v_mfma_f32_32x32x16_bf16 v[16:31], v[56:59], v[44:47], v[16:31]
	ds_read_b128 v[48:51], v209 offset:57344
	v_mfma_f32_32x32x16_bf16 v[0:15], v[32:35], v[44:47], v[0:15]
	ds_read_b128 v[56:59], v209 offset:61440
	v_mfma_f32_32x32x16_bf16 v[80:95], v[36:39], v[52:55], v[80:95]
	v_mfma_f32_32x32x16_bf16 v[64:79], v[40:43], v[52:55], v[64:79]
	s_waitcnt lgkmcnt(0)
	v_mfma_f32_32x32x16_bf16 v[16:31], v[48:51], v[52:55], v[16:31]
	v_mfma_f32_32x32x16_bf16 v[0:15], v[56:59], v[52:55], v[0:15]
	s_waitcnt vmcnt(4) lgkmcnt(0)
	s_barrier
	s_mov_b32 s44, s14
	s_add_i32 s44, s44, s15
	s_sub_i32 s44, s44, 64
	s_ashr_i32 s45, s44, 31
	s_lshl_b64 s[44:45], s[44:45], 1
	s_add_u32 s44, s39, s44
	s_addc_u32 s45, s67, s45
	s_add_i32 s49, s58, 0xc000
	s_add_i32 m0, s49, 0xc000
	s_nop 0
	global_load_lds_dwordx4 v196, s[44:45]
	s_add_i32 m0, s49, 0xc400
	s_nop 0
	global_load_lds_dwordx4 v192, s[44:45]
	v_exp_f32_e32 v144, v112
	ds_read_b128 v[32:35], v205
	ds_read_b128 v[36:39], v205 offset:8192
	v_exp_f32_e32 v145, v113
	v_exp_f32_e32 v146, v114
	v_exp_f32_e32 v147, v115
	s_waitcnt lgkmcnt(0)
	v_mfma_f32_32x32x16_bf16 v[48:63], v[32:35], v[160:163], 0
	ds_read_b128 v[132:135], v211
	ds_read_b128 v[136:139], v211 offset:8192
	ds_read_b128 v[140:143], v212
	ds_read_b128 v[112:115], v212 offset:8192
	v_mfma_f32_32x32x16_bf16 v[32:47], v[36:39], v[160:163], 0
	v_exp_f32_e32 v148, v116
	v_exp_f32_e32 v149, v117
	v_exp_f32_e32 v150, v118
	v_exp_f32_e32 v151, v119
	s_waitcnt lgkmcnt(0)
	v_mfma_f32_32x32x16_bf16 v[48:63], v[132:135], v[164:167], v[48:63]
	ds_read_b128 v[116:119], v213
	v_exp_f32_e32 v152, v120
	v_exp_f32_e32 v153, v121
	v_exp_f32_e32 v154, v122
	v_exp_f32_e32 v155, v123
	v_mfma_f32_32x32x16_bf16 v[32:47], v[136:139], v[164:167], v[32:47]
	ds_read_b128 v[120:123], v213 offset:8192
	v_exp_f32_e32 v156, v124
	v_exp_f32_e32 v157, v125
	v_exp_f32_e32 v158, v126
	v_exp_f32_e32 v159, v127
	v_mfma_f32_32x32x16_bf16 v[48:63], v[140:143], v[168:171], v[48:63]
	ds_read_b128 v[124:127], v236
	v_exp_f32_e32 v136, v96
	v_exp_f32_e32 v137, v97
	v_exp_f32_e32 v138, v98
	v_exp_f32_e32 v139, v99
	v_mfma_f32_32x32x16_bf16 v[32:47], v[112:115], v[168:171], v[32:47]
	ds_read_b128 v[96:99], v236 offset:4096
	v_exp_f32_e32 v140, v100
	v_exp_f32_e32 v141, v101
	v_exp_f32_e32 v142, v102
	v_exp_f32_e32 v143, v103
	s_waitcnt lgkmcnt(0)
	v_mfma_f32_32x32x16_bf16 v[48:63], v[116:119], v[172:175], v[48:63]
	ds_read_b128 v[100:103], v236 offset:8192
	v_exp_f32_e32 v178, v104
	v_exp_f32_e32 v179, v105
	v_exp_f32_e32 v180, v106
	v_exp_f32_e32 v181, v107
	v_mfma_f32_32x32x16_bf16 v[32:47], v[120:123], v[172:175], v[32:47]
	ds_read_b128 v[104:107], v236 offset:12288
	v_exp_f32_e32 v182, v108
	v_exp_f32_e32 v183, v109
	v_exp_f32_e32 v184, v110
	v_exp_f32_e32 v185, v111
	v_cvt_pk_bf16_f32 v108, v144, v145
	v_cvt_pk_bf16_f32 v109, v146, v147
	v_cvt_pk_bf16_f32 v110, v148, v149
	v_cvt_pk_bf16_f32 v111, v150, v151
	s_nop 1
	v_mfma_f32_32x32x16_bf16 v[80:95], v[124:127], v[108:111], v[80:95]
	ds_read_b128 v[112:115], v237
	v_cvt_pk_bf16_f32 v116, v152, v153
	v_cvt_pk_bf16_f32 v117, v154, v155
	v_cvt_pk_bf16_f32 v118, v156, v157
	v_cvt_pk_bf16_f32 v119, v158, v159
	v_mfma_f32_32x32x16_bf16 v[64:79], v[96:99], v[108:111], v[64:79]
	ds_read_b128 v[120:123], v237 offset:4096
	v_pk_add_f32 v[126:127], v[150:151], v[146:147]
	v_pk_add_f32 v[124:125], v[148:149], v[144:145]
	s_waitcnt lgkmcnt(0)
	v_mfma_f32_32x32x16_bf16 v[16:31], v[100:103], v[108:111], v[16:31]
	ds_read_b128 v[132:135], v237 offset:8192
	v_add_f32_e64 v98, v154, v126
	v_add_f32_e64 v99, v155, v127
	v_add_f32_e64 v96, v152, v124
	v_add_f32_e64 v97, v153, v125
	v_pk_add_f32 v[98:99], v[158:159], v[98:99]
	v_pk_add_f32 v[96:97], v[156:157], v[96:97]
	v_mfma_f32_32x32x16_bf16 v[0:15], v[104:107], v[108:111], v[0:15]
	ds_read_b128 v[100:103], v237 offset:12288
	v_mfma_f32_32x32x16_bf16 v[80:95], v[112:115], v[116:119], v[80:95]
	ds_read_b128 v[104:107], v238
	v_cvt_pk_bf16_f32 v108, v136, v137
	v_cvt_pk_bf16_f32 v109, v138, v139
	v_cvt_pk_bf16_f32 v110, v140, v141
	v_cvt_pk_bf16_f32 v111, v142, v143
	v_mfma_f32_32x32x16_bf16 v[64:79], v[120:123], v[116:119], v[64:79]
	ds_read_b128 v[112:115], v238 offset:4096
	v_add_f32_e64 v98, v138, v98
	v_add_f32_e64 v99, v139, v99
	v_add_f32_e64 v96, v136, v96
	v_add_f32_e64 v97, v137, v97
	v_pk_add_f32 v[98:99], v[142:143], v[98:99]
	v_pk_add_f32 v[96:97], v[140:141], v[96:97]
	s_waitcnt lgkmcnt(0)
	v_mfma_f32_32x32x16_bf16 v[16:31], v[132:135], v[116:119], v[16:31]
	ds_read_b128 v[120:123], v238 offset:8192
	v_add_f32_e64 v98, v180, v98
	v_add_f32_e64 v99, v181, v99
	v_add_f32_e64 v96, v178, v96
	v_add_f32_e64 v97, v179, v97
	v_pk_add_f32 v[98:99], v[184:185], v[98:99]
	v_pk_add_f32 v[96:97], v[182:183], v[96:97]
	v_mfma_f32_32x32x16_bf16 v[0:15], v[100:103], v[116:119], v[0:15]
	ds_read_b128 v[124:127], v238 offset:12288
	v_mfma_f32_32x32x16_bf16 v[80:95], v[104:107], v[108:111], v[80:95]
	ds_read_b128 v[100:103], v239
	v_cvt_pk_bf16_f32 v116, v178, v179
	v_cvt_pk_bf16_f32 v117, v180, v181
	v_cvt_pk_bf16_f32 v118, v182, v183
	v_cvt_pk_bf16_f32 v119, v184, v185
	v_mfma_f32_32x32x16_bf16 v[64:79], v[112:115], v[108:111], v[64:79]
	ds_read_b128 v[104:107], v239 offset:4096
	s_waitcnt lgkmcnt(0)
	v_mfma_f32_32x32x16_bf16 v[16:31], v[120:123], v[108:111], v[16:31]
	ds_read_b128 v[112:115], v239 offset:8192
	v_mfma_f32_32x32x16_bf16 v[0:15], v[124:127], v[108:111], v[0:15]
	ds_read_b128 v[120:123], v239 offset:12288
	v_mfma_f32_32x32x16_bf16 v[80:95], v[100:103], v[116:119], v[80:95]
	v_mfma_f32_32x32x16_bf16 v[64:79], v[104:107], v[116:119], v[64:79]
	s_waitcnt lgkmcnt(0)
	v_mfma_f32_32x32x16_bf16 v[16:31], v[112:115], v[116:119], v[16:31]
	v_mfma_f32_32x32x16_bf16 v[0:15], v[120:123], v[116:119], v[0:15]
	s_waitcnt vmcnt(2) lgkmcnt(0)
	v_add_f32_e32 v100, v128, v129
	v_add_f32_e32 v101, v130, v131
	v_add_f32_e32 v100, v100, v101
	v_add_f32_e32 v96, v96, v97
	v_add_f32_e32 v97, v98, v99
	s_barrier
	v_add_f32_e32 v100, v177, v100
	v_add_f32_e32 v96, v96, v97
	v_add_f32_e32 v177, v100, v96
	s_add_i32 s21, s21, 2
	s_addk_i32 s15, 0x80
	s_add_i32 s20, s20, 0x8000
	s_add_i32 s46, s20, 0xffff4000
	ds_read_b128 v[96:99], v205 offset:16384
	ds_read_b128 v[100:103], v205 offset:24576
	v_exp_f32_e32 v140, v48
	v_exp_f32_e32 v141, v49
	v_exp_f32_e32 v142, v50
	v_exp_f32_e32 v143, v51
	s_waitcnt lgkmcnt(0)
	v_mfma_f32_32x32x16_bf16 v[112:127], v[96:99], v[160:163], 0
	ds_read_b128 v[128:131], v211 offset:16384
	ds_read_b128 v[132:135], v211 offset:24576
	ds_read_b128 v[136:139], v212 offset:16384
	ds_read_b128 v[48:51], v212 offset:24576
	v_mfma_f32_32x32x16_bf16 v[96:111], v[100:103], v[160:163], 0
	v_exp_f32_e32 v144, v52
	v_exp_f32_e32 v145, v53
	v_exp_f32_e32 v146, v54
	v_exp_f32_e32 v147, v55
	s_waitcnt lgkmcnt(0)
	v_mfma_f32_32x32x16_bf16 v[112:127], v[128:131], v[164:167], v[112:127]
	ds_read_b128 v[52:55], v213 offset:16384
	v_exp_f32_e32 v148, v56
	v_exp_f32_e32 v149, v57
	v_exp_f32_e32 v150, v58
	v_exp_f32_e32 v151, v59
	v_mfma_f32_32x32x16_bf16 v[96:111], v[132:135], v[164:167], v[96:111]
	ds_read_b128 v[56:59], v213 offset:24576
	v_exp_f32_e32 v128, v60
	v_exp_f32_e32 v129, v61
	v_exp_f32_e32 v130, v62
	v_exp_f32_e32 v131, v63
	v_mfma_f32_32x32x16_bf16 v[112:127], v[136:139], v[168:171], v[112:127]
	ds_read_b128 v[60:63], v236 offset:16384
	v_exp_f32_e32 v132, v32
	v_exp_f32_e32 v133, v33
	v_exp_f32_e32 v134, v34
	v_exp_f32_e32 v135, v35
	v_mfma_f32_32x32x16_bf16 v[96:111], v[48:51], v[168:171], v[96:111]
	ds_read_b128 v[32:35], v236 offset:20480
	v_exp_f32_e32 v136, v36
	v_exp_f32_e32 v137, v37
	v_exp_f32_e32 v138, v38
	v_exp_f32_e32 v139, v39
	s_waitcnt lgkmcnt(0)
	v_mfma_f32_32x32x16_bf16 v[112:127], v[52:55], v[172:175], v[112:127]
	ds_read_b128 v[36:39], v236 offset:24576
	v_exp_f32_e32 v152, v40
	v_exp_f32_e32 v153, v41
	v_exp_f32_e32 v154, v42
	v_exp_f32_e32 v155, v43
	v_mfma_f32_32x32x16_bf16 v[96:111], v[56:59], v[172:175], v[96:111]
	ds_read_b128 v[40:43], v236 offset:28672
	v_exp_f32_e32 v156, v44
	v_exp_f32_e32 v157, v45
	v_exp_f32_e32 v158, v46
	v_exp_f32_e32 v159, v47
	v_cvt_pk_bf16_f32 v44, v140, v141
	v_cvt_pk_bf16_f32 v45, v142, v143
	v_cvt_pk_bf16_f32 v46, v144, v145
	v_cvt_pk_bf16_f32 v47, v146, v147
	s_nop 1
	v_mfma_f32_32x32x16_bf16 v[80:95], v[60:63], v[44:47], v[80:95]
	ds_read_b128 v[48:51], v237 offset:16384
	v_cvt_pk_bf16_f32 v52, v148, v149
	v_cvt_pk_bf16_f32 v53, v150, v151
	v_cvt_pk_bf16_f32 v54, v128, v129
	v_cvt_pk_bf16_f32 v55, v130, v131
	v_mfma_f32_32x32x16_bf16 v[64:79], v[32:35], v[44:47], v[64:79]
	ds_read_b128 v[56:59], v237 offset:20480
	v_pk_add_f32 v[62:63], v[146:147], v[142:143]
	v_pk_add_f32 v[60:61], v[144:145], v[140:141]
	s_waitcnt lgkmcnt(0)
	v_mfma_f32_32x32x16_bf16 v[16:31], v[36:39], v[44:47], v[16:31]
	ds_read_b128 v[32:35], v237 offset:24576
	v_add_f32_e64 v62, v150, v62
	v_add_f32_e64 v63, v151, v63
	v_add_f32_e64 v60, v148, v60
	v_add_f32_e64 v61, v149, v61
	v_pk_add_f32 v[62:63], v[130:131], v[62:63]
	v_pk_add_f32 v[60:61], v[128:129], v[60:61]
	v_mfma_f32_32x32x16_bf16 v[0:15], v[40:43], v[44:47], v[0:15]
	ds_read_b128 v[36:39], v237 offset:28672
	v_mfma_f32_32x32x16_bf16 v[80:95], v[48:51], v[52:55], v[80:95]
	ds_read_b128 v[40:43], v238 offset:16384
	v_cvt_pk_bf16_f32 v44, v132, v133
	v_cvt_pk_bf16_f32 v45, v134, v135
	v_cvt_pk_bf16_f32 v46, v136, v137
	v_cvt_pk_bf16_f32 v47, v138, v139
	v_mfma_f32_32x32x16_bf16 v[64:79], v[56:59], v[52:55], v[64:79]
	ds_read_b128 v[48:51], v238 offset:20480
	v_add_f32_e64 v62, v134, v62
	v_add_f32_e64 v63, v135, v63
	v_add_f32_e64 v60, v132, v60
	v_add_f32_e64 v61, v133, v61
	v_pk_add_f32 v[62:63], v[138:139], v[62:63]
	v_pk_add_f32 v[60:61], v[136:137], v[60:61]
	s_waitcnt lgkmcnt(0)
	v_mfma_f32_32x32x16_bf16 v[16:31], v[32:35], v[52:55], v[16:31]
	ds_read_b128 v[56:59], v238 offset:24576
	v_add_f32_e64 v62, v154, v62
	v_add_f32_e64 v63, v155, v63
	v_add_f32_e64 v60, v152, v60
	v_add_f32_e64 v61, v153, v61
	v_pk_add_f32 v[130:131], v[158:159], v[62:63]
	v_pk_add_f32 v[128:129], v[156:157], v[60:61]
	v_mfma_f32_32x32x16_bf16 v[0:15], v[36:39], v[52:55], v[0:15]
	ds_read_b128 v[32:35], v238 offset:28672
	v_mfma_f32_32x32x16_bf16 v[80:95], v[40:43], v[44:47], v[80:95]
	ds_read_b128 v[36:39], v239 offset:16384
	v_cvt_pk_bf16_f32 v52, v152, v153
	v_cvt_pk_bf16_f32 v53, v154, v155
	v_cvt_pk_bf16_f32 v54, v156, v157
	v_cvt_pk_bf16_f32 v55, v158, v159
	v_mfma_f32_32x32x16_bf16 v[64:79], v[48:51], v[44:47], v[64:79]
	ds_read_b128 v[40:43], v239 offset:20480
	s_waitcnt lgkmcnt(0)
	v_mfma_f32_32x32x16_bf16 v[16:31], v[56:59], v[44:47], v[16:31]
	ds_read_b128 v[48:51], v239 offset:24576
	v_mfma_f32_32x32x16_bf16 v[0:15], v[32:35], v[44:47], v[0:15]
	ds_read_b128 v[56:59], v239 offset:28672
	v_mfma_f32_32x32x16_bf16 v[80:95], v[36:39], v[52:55], v[80:95]
	v_mfma_f32_32x32x16_bf16 v[64:79], v[40:43], v[52:55], v[64:79]
	s_waitcnt lgkmcnt(0)
	v_mfma_f32_32x32x16_bf16 v[16:31], v[48:51], v[52:55], v[16:31]
	v_mfma_f32_32x32x16_bf16 v[0:15], v[56:59], v[52:55], v[0:15]
	s_waitcnt vmcnt(0) lgkmcnt(0)
	s_barrier
	v_exp_f32_e32 v144, v112
	ds_read_b128 v[32:35], v205 offset:32768
	ds_read_b128 v[36:39], v205 offset:40960
	v_exp_f32_e32 v145, v113
	v_exp_f32_e32 v146, v114
	v_exp_f32_e32 v147, v115
	s_waitcnt lgkmcnt(0)
	v_mfma_f32_32x32x16_bf16 v[48:63], v[32:35], v[160:163], 0
	ds_read_b128 v[132:135], v211 offset:32768
	ds_read_b128 v[136:139], v211 offset:40960
	ds_read_b128 v[140:143], v212 offset:32768
	ds_read_b128 v[112:115], v212 offset:40960
	v_mfma_f32_32x32x16_bf16 v[32:47], v[36:39], v[160:163], 0
	v_exp_f32_e32 v148, v116
	v_exp_f32_e32 v149, v117
	v_exp_f32_e32 v150, v118
	v_exp_f32_e32 v151, v119
	s_waitcnt lgkmcnt(0)
	v_mfma_f32_32x32x16_bf16 v[48:63], v[132:135], v[164:167], v[48:63]
	ds_read_b128 v[116:119], v213 offset:32768
	v_exp_f32_e32 v152, v120
	v_exp_f32_e32 v153, v121
	v_exp_f32_e32 v154, v122
	v_exp_f32_e32 v155, v123
	v_mfma_f32_32x32x16_bf16 v[32:47], v[136:139], v[164:167], v[32:47]
	ds_read_b128 v[120:123], v213 offset:40960
	v_exp_f32_e32 v156, v124
	v_exp_f32_e32 v157, v125
	v_exp_f32_e32 v158, v126
	v_exp_f32_e32 v159, v127
	v_mfma_f32_32x32x16_bf16 v[48:63], v[140:143], v[168:171], v[48:63]
	ds_read_b128 v[124:127], v236 offset:32768
	v_exp_f32_e32 v136, v96
	v_exp_f32_e32 v137, v97
	v_exp_f32_e32 v138, v98
	v_exp_f32_e32 v139, v99
	v_mfma_f32_32x32x16_bf16 v[32:47], v[112:115], v[168:171], v[32:47]
	ds_read_b128 v[96:99], v236 offset:36864
	v_exp_f32_e32 v140, v100
	v_exp_f32_e32 v141, v101
	v_exp_f32_e32 v142, v102
	v_exp_f32_e32 v143, v103
	s_waitcnt lgkmcnt(0)
	v_mfma_f32_32x32x16_bf16 v[48:63], v[116:119], v[172:175], v[48:63]
	ds_read_b128 v[100:103], v236 offset:40960
	v_exp_f32_e32 v178, v104
	v_exp_f32_e32 v179, v105
	v_exp_f32_e32 v180, v106
	v_exp_f32_e32 v181, v107
	v_mfma_f32_32x32x16_bf16 v[32:47], v[120:123], v[172:175], v[32:47]
	ds_read_b128 v[104:107], v236 offset:45056
	v_exp_f32_e32 v182, v108
	v_exp_f32_e32 v183, v109
	v_exp_f32_e32 v184, v110
	v_exp_f32_e32 v185, v111
	v_cvt_pk_bf16_f32 v108, v144, v145
	v_cvt_pk_bf16_f32 v109, v146, v147
	v_cvt_pk_bf16_f32 v110, v148, v149
	v_cvt_pk_bf16_f32 v111, v150, v151
	s_nop 1
	v_mfma_f32_32x32x16_bf16 v[80:95], v[124:127], v[108:111], v[80:95]
	ds_read_b128 v[112:115], v237 offset:32768
	v_cvt_pk_bf16_f32 v116, v152, v153
	v_cvt_pk_bf16_f32 v117, v154, v155
	v_cvt_pk_bf16_f32 v118, v156, v157
	v_cvt_pk_bf16_f32 v119, v158, v159
	v_mfma_f32_32x32x16_bf16 v[64:79], v[96:99], v[108:111], v[64:79]
	ds_read_b128 v[120:123], v237 offset:36864
	v_pk_add_f32 v[126:127], v[150:151], v[146:147]
	v_pk_add_f32 v[124:125], v[148:149], v[144:145]
	s_waitcnt lgkmcnt(0)
	v_mfma_f32_32x32x16_bf16 v[16:31], v[100:103], v[108:111], v[16:31]
	ds_read_b128 v[132:135], v237 offset:40960
	v_add_f32_e64 v98, v154, v126
	v_add_f32_e64 v99, v155, v127
	v_add_f32_e64 v96, v152, v124
	v_add_f32_e64 v97, v153, v125
	v_pk_add_f32 v[98:99], v[158:159], v[98:99]
	v_pk_add_f32 v[96:97], v[156:157], v[96:97]
	v_mfma_f32_32x32x16_bf16 v[0:15], v[104:107], v[108:111], v[0:15]
	ds_read_b128 v[100:103], v237 offset:45056
	v_mfma_f32_32x32x16_bf16 v[80:95], v[112:115], v[116:119], v[80:95]
	ds_read_b128 v[104:107], v238 offset:32768
	v_cvt_pk_bf16_f32 v108, v136, v137
	v_cvt_pk_bf16_f32 v109, v138, v139
	v_cvt_pk_bf16_f32 v110, v140, v141
	v_cvt_pk_bf16_f32 v111, v142, v143
	v_mfma_f32_32x32x16_bf16 v[64:79], v[120:123], v[116:119], v[64:79]
	ds_read_b128 v[112:115], v238 offset:36864
	v_add_f32_e64 v98, v138, v98
	v_add_f32_e64 v99, v139, v99
	v_add_f32_e64 v96, v136, v96
	v_add_f32_e64 v97, v137, v97
	v_pk_add_f32 v[98:99], v[142:143], v[98:99]
	v_pk_add_f32 v[96:97], v[140:141], v[96:97]
	s_waitcnt lgkmcnt(0)
	v_mfma_f32_32x32x16_bf16 v[16:31], v[132:135], v[116:119], v[16:31]
	ds_read_b128 v[120:123], v238 offset:40960
	v_add_f32_e64 v98, v180, v98
	v_add_f32_e64 v99, v181, v99
	v_add_f32_e64 v96, v178, v96
	v_add_f32_e64 v97, v179, v97
	v_pk_add_f32 v[98:99], v[184:185], v[98:99]
	v_pk_add_f32 v[96:97], v[182:183], v[96:97]
	v_mfma_f32_32x32x16_bf16 v[0:15], v[100:103], v[116:119], v[0:15]
	ds_read_b128 v[124:127], v238 offset:45056
	v_mfma_f32_32x32x16_bf16 v[80:95], v[104:107], v[108:111], v[80:95]
	ds_read_b128 v[100:103], v239 offset:32768
	v_cvt_pk_bf16_f32 v116, v178, v179
	v_cvt_pk_bf16_f32 v117, v180, v181
	v_cvt_pk_bf16_f32 v118, v182, v183
	v_cvt_pk_bf16_f32 v119, v184, v185
	v_mfma_f32_32x32x16_bf16 v[64:79], v[112:115], v[108:111], v[64:79]
	ds_read_b128 v[104:107], v239 offset:36864
	s_waitcnt lgkmcnt(0)
	v_mfma_f32_32x32x16_bf16 v[16:31], v[120:123], v[108:111], v[16:31]
	ds_read_b128 v[112:115], v239 offset:40960
	v_mfma_f32_32x32x16_bf16 v[0:15], v[124:127], v[108:111], v[0:15]
	ds_read_b128 v[120:123], v239 offset:45056
	v_mfma_f32_32x32x16_bf16 v[80:95], v[100:103], v[116:119], v[80:95]
	v_mfma_f32_32x32x16_bf16 v[64:79], v[104:107], v[116:119], v[64:79]
	s_waitcnt lgkmcnt(0)
	v_mfma_f32_32x32x16_bf16 v[16:31], v[112:115], v[116:119], v[16:31]
	v_mfma_f32_32x32x16_bf16 v[0:15], v[120:123], v[116:119], v[0:15]
	s_waitcnt vmcnt(0) lgkmcnt(0)
	v_add_f32_e32 v100, v128, v129
	v_add_f32_e32 v101, v130, v131
	v_add_f32_e32 v100, v100, v101
	v_add_f32_e32 v96, v96, v97
	v_add_f32_e32 v97, v98, v99
	s_barrier
	v_add_f32_e32 v100, v177, v100
	v_add_f32_e32 v96, v96, v97
	v_add_f32_e32 v177, v100, v96
	s_add_i32 s21, s21, 2
	s_addk_i32 s15, 0x80
	s_add_i32 s20, s20, 0x8000
	s_branch .LBB0_960
